# adds: fully serialized gain loads of layer-1 weight conversion hoisted; v-column epilogue row-norm loads hoisted
# speedup vs baseline: 1.0150x; 1.0031x over previous
.LBB0_111:
	v_mov_b64_e32 v[130:131], s[24:25]
	v_mad_i64_i32 v[134:135], s[0:1], v174, s91, v[130:131]
	v_lshlrev_b64 v[132:133], 1, v[176:177]
	v_lshl_add_u64 v[136:137], v[134:135], 0, v[132:133]
	v_lshl_add_u64 v[134:135], v[174:175], 2, s[40:41]
	global_load_dword v140, v[134:135], off
	global_load_dword v141, v[134:135], off offset:64
	global_load_dword v142, v[134:135], off offset:128
	global_load_dword v143, v[134:135], off offset:192
	global_load_dword v144, v[134:135], off offset:512
	global_load_dword v145, v[134:135], off offset:576
	global_load_dword v146, v[134:135], off offset:640
	global_load_dword v147, v[134:135], off offset:704
	s_waitcnt vmcnt(0)
	v_fmamk_f32 v0, v140, 0x3a800000, v214
	v_cmp_gt_f32_e32 vcc, s90, v0
	v_mul_f32_e32 v138, 0x4b800000, v0
	s_nop 0
	v_cndmask_b32_e32 v0, v0, v138, vcc
	v_rsq_f32_e32 v0, v0
	s_nop 0
	v_mul_f32_e32 v138, 0x45800000, v0
	v_cndmask_b32_e32 v0, v0, v138, vcc
	v_pk_mul_f32 v[128:129], v[128:129], v[0:1] op_sel_hi:[1,0]
	v_pk_mul_f32 v[126:127], v[126:127], v[0:1] op_sel_hi:[1,0]
	v_pk_mul_f32 v[138:139], v[124:125], v[0:1] op_sel_hi:[1,0]
	v_pk_mul_f32 v[124:125], v[122:123], v[0:1] op_sel_hi:[1,0]
	v_cvt_pk_bf16_f32 v122, v126, v127
	v_cvt_pk_bf16_f32 v123, v128, v129
	v_pk_mul_f32 v[120:121], v[120:121], v[0:1] op_sel_hi:[1,0]
	v_cvt_pk_bf16_f32 v124, v124, v125
	v_cvt_pk_bf16_f32 v125, v138, v139
	global_store_dwordx4 v[136:137], v[122:125], off
	v_pk_mul_f32 v[118:119], v[118:119], v[0:1] op_sel_hi:[1,0]
	s_nop 0
	v_pk_mul_f32 v[122:123], v[116:117], v[0:1] op_sel_hi:[1,0]
	v_pk_mul_f32 v[116:117], v[114:115], v[0:1] op_sel_hi:[1,0]
	v_cvt_pk_bf16_f32 v114, v118, v119
	v_cvt_pk_bf16_f32 v115, v120, v121
	s_nop 0
	v_cvt_pk_bf16_f32 v116, v116, v117
	v_cvt_pk_bf16_f32 v117, v122, v123
	global_store_dwordx4 v[136:137], v[114:117], off offset:64
	v_fmamk_f32 v0, v141, 0x3a800000, v214
	v_cmp_gt_f32_e32 vcc, s90, v0
	v_mul_f32_e32 v116, 0x4b800000, v0
	v_mad_i64_i32 v[114:115], s[0:1], v193, s91, v[130:131]
	v_cndmask_b32_e32 v0, v0, v116, vcc
	v_rsq_f32_e32 v0, v0
	v_lshl_add_u64 v[114:115], v[114:115], 0, v[132:133]
	v_mul_f32_e32 v116, 0x45800000, v0
	v_cndmask_b32_e32 v0, v0, v116, vcc
	v_pk_mul_f32 v[112:113], v[112:113], v[0:1] op_sel_hi:[1,0]
	v_pk_mul_f32 v[110:111], v[110:111], v[0:1] op_sel_hi:[1,0]
	v_pk_mul_f32 v[116:117], v[108:109], v[0:1] op_sel_hi:[1,0]
	v_pk_mul_f32 v[108:109], v[106:107], v[0:1] op_sel_hi:[1,0]
	v_cvt_pk_bf16_f32 v106, v110, v111
	v_cvt_pk_bf16_f32 v107, v112, v113
	v_pk_mul_f32 v[104:105], v[104:105], v[0:1] op_sel_hi:[1,0]
	v_cvt_pk_bf16_f32 v108, v108, v109
	v_cvt_pk_bf16_f32 v109, v116, v117
	global_store_dwordx4 v[114:115], v[106:109], off
	v_pk_mul_f32 v[102:103], v[102:103], v[0:1] op_sel_hi:[1,0]
	s_nop 0
	v_pk_mul_f32 v[106:107], v[100:101], v[0:1] op_sel_hi:[1,0]
	v_pk_mul_f32 v[100:101], v[98:99], v[0:1] op_sel_hi:[1,0]
	v_cvt_pk_bf16_f32 v98, v102, v103
	v_cvt_pk_bf16_f32 v99, v104, v105
	s_nop 0
	v_cvt_pk_bf16_f32 v100, v100, v101
	v_cvt_pk_bf16_f32 v101, v106, v107
	global_store_dwordx4 v[114:115], v[98:101], off offset:64
	v_fmamk_f32 v0, v142, 0x3a800000, v214
	v_cmp_gt_f32_e32 vcc, s90, v0
	v_mul_f32_e32 v100, 0x4b800000, v0
	v_mad_i64_i32 v[98:99], s[0:1], v192, s91, v[130:131]
	v_cndmask_b32_e32 v0, v0, v100, vcc
	v_rsq_f32_e32 v0, v0
	v_lshl_add_u64 v[98:99], v[98:99], 0, v[132:133]
	v_mul_f32_e32 v100, 0x45800000, v0
	v_cndmask_b32_e32 v0, v0, v100, vcc
	v_pk_mul_f32 v[96:97], v[96:97], v[0:1] op_sel_hi:[1,0]
	v_pk_mul_f32 v[94:95], v[94:95], v[0:1] op_sel_hi:[1,0]
	v_pk_mul_f32 v[100:101], v[92:93], v[0:1] op_sel_hi:[1,0]
	v_pk_mul_f32 v[92:93], v[90:91], v[0:1] op_sel_hi:[1,0]
	v_cvt_pk_bf16_f32 v90, v94, v95
	v_cvt_pk_bf16_f32 v91, v96, v97
	v_pk_mul_f32 v[88:89], v[88:89], v[0:1] op_sel_hi:[1,0]
	v_cvt_pk_bf16_f32 v92, v92, v93
	v_cvt_pk_bf16_f32 v93, v100, v101
	global_store_dwordx4 v[98:99], v[90:93], off
	v_pk_mul_f32 v[86:87], v[86:87], v[0:1] op_sel_hi:[1,0]
	s_nop 0
	v_pk_mul_f32 v[90:91], v[84:85], v[0:1] op_sel_hi:[1,0]
	v_pk_mul_f32 v[84:85], v[82:83], v[0:1] op_sel_hi:[1,0]
	v_cvt_pk_bf16_f32 v82, v86, v87
	v_cvt_pk_bf16_f32 v83, v88, v89
	s_nop 0
	v_cvt_pk_bf16_f32 v84, v84, v85
	v_cvt_pk_bf16_f32 v85, v90, v91
	global_store_dwordx4 v[98:99], v[82:85], off offset:64
	v_fmamk_f32 v0, v143, 0x3a800000, v214
	v_cmp_gt_f32_e32 vcc, s90, v0
	v_mul_f32_e32 v84, 0x4b800000, v0
	v_mad_i64_i32 v[82:83], s[0:1], v191, s91, v[130:131]
	v_cndmask_b32_e32 v0, v0, v84, vcc
	v_rsq_f32_e32 v0, v0
	v_lshl_add_u64 v[82:83], v[82:83], 0, v[132:133]
	v_mul_f32_e32 v84, 0x45800000, v0
	v_cndmask_b32_e32 v0, v0, v84, vcc
	v_pk_mul_f32 v[80:81], v[80:81], v[0:1] op_sel_hi:[1,0]
	v_pk_mul_f32 v[78:79], v[78:79], v[0:1] op_sel_hi:[1,0]
	v_pk_mul_f32 v[84:85], v[76:77], v[0:1] op_sel_hi:[1,0]
	v_pk_mul_f32 v[76:77], v[74:75], v[0:1] op_sel_hi:[1,0]
	v_cvt_pk_bf16_f32 v74, v78, v79
	v_cvt_pk_bf16_f32 v75, v80, v81
	v_pk_mul_f32 v[72:73], v[72:73], v[0:1] op_sel_hi:[1,0]
	v_cvt_pk_bf16_f32 v76, v76, v77
	v_cvt_pk_bf16_f32 v77, v84, v85
	global_store_dwordx4 v[82:83], v[74:77], off
	v_pk_mul_f32 v[70:71], v[70:71], v[0:1] op_sel_hi:[1,0]
	s_nop 0
	v_pk_mul_f32 v[74:75], v[68:69], v[0:1] op_sel_hi:[1,0]
	v_pk_mul_f32 v[68:69], v[66:67], v[0:1] op_sel_hi:[1,0]
	v_cvt_pk_bf16_f32 v66, v70, v71
	v_cvt_pk_bf16_f32 v67, v72, v73
	v_add_u32_e32 v0, 0x80, v174
	v_cvt_pk_bf16_f32 v68, v68, v69
	v_cvt_pk_bf16_f32 v69, v74, v75
	global_store_dwordx4 v[82:83], v[66:69], off offset:64
	s_nop 1
	v_mad_i64_i32 v[66:67], s[0:1], v0, s91, v[130:131]
	v_lshl_add_u64 v[66:67], v[66:67], 0, v[132:133]
	v_fmamk_f32 v0, v144, 0x3a800000, v214
	v_cmp_gt_f32_e32 vcc, s90, v0
	v_mul_f32_e32 v68, 0x4b800000, v0
	s_nop 0
	v_cndmask_b32_e32 v0, v0, v68, vcc
	v_rsq_f32_e32 v0, v0
	s_nop 0
	v_mul_f32_e32 v68, 0x45800000, v0
	v_cndmask_b32_e32 v0, v0, v68, vcc
	v_pk_mul_f32 v[64:65], v[64:65], v[0:1] op_sel_hi:[1,0]
	v_pk_mul_f32 v[62:63], v[62:63], v[0:1] op_sel_hi:[1,0]
	v_pk_mul_f32 v[68:69], v[60:61], v[0:1] op_sel_hi:[1,0]
	v_pk_mul_f32 v[60:61], v[58:59], v[0:1] op_sel_hi:[1,0]
	v_cvt_pk_bf16_f32 v58, v62, v63
	v_cvt_pk_bf16_f32 v59, v64, v65
	v_pk_mul_f32 v[56:57], v[56:57], v[0:1] op_sel_hi:[1,0]
	v_cvt_pk_bf16_f32 v60, v60, v61
	v_cvt_pk_bf16_f32 v61, v68, v69
	global_store_dwordx4 v[66:67], v[58:61], off
	v_pk_mul_f32 v[54:55], v[54:55], v[0:1] op_sel_hi:[1,0]
	s_nop 0
	v_pk_mul_f32 v[58:59], v[52:53], v[0:1] op_sel_hi:[1,0]
	v_pk_mul_f32 v[52:53], v[50:51], v[0:1] op_sel_hi:[1,0]
	v_cvt_pk_bf16_f32 v50, v54, v55
	v_cvt_pk_bf16_f32 v51, v56, v57
	v_add_u32_e32 v0, 0x90, v174
	v_cvt_pk_bf16_f32 v52, v52, v53
	v_cvt_pk_bf16_f32 v53, v58, v59
	global_store_dwordx4 v[66:67], v[50:53], off offset:64
	s_nop 1
	v_mad_i64_i32 v[50:51], s[0:1], v0, s91, v[130:131]
	v_lshl_add_u64 v[50:51], v[50:51], 0, v[132:133]
	v_fmamk_f32 v0, v145, 0x3a800000, v214
	v_cmp_gt_f32_e32 vcc, s90, v0
	v_mul_f32_e32 v52, 0x4b800000, v0
	s_nop 0
	v_cndmask_b32_e32 v0, v0, v52, vcc
	v_rsq_f32_e32 v0, v0
	s_nop 0
	v_mul_f32_e32 v52, 0x45800000, v0
	v_cndmask_b32_e32 v0, v0, v52, vcc
	v_pk_mul_f32 v[48:49], v[48:49], v[0:1] op_sel_hi:[1,0]
	v_pk_mul_f32 v[46:47], v[46:47], v[0:1] op_sel_hi:[1,0]
	v_pk_mul_f32 v[52:53], v[44:45], v[0:1] op_sel_hi:[1,0]
	v_pk_mul_f32 v[44:45], v[42:43], v[0:1] op_sel_hi:[1,0]
	v_cvt_pk_bf16_f32 v42, v46, v47
	v_cvt_pk_bf16_f32 v43, v48, v49
	v_pk_mul_f32 v[40:41], v[40:41], v[0:1] op_sel_hi:[1,0]
	v_cvt_pk_bf16_f32 v44, v44, v45
	v_cvt_pk_bf16_f32 v45, v52, v53
	global_store_dwordx4 v[50:51], v[42:45], off
	v_pk_mul_f32 v[38:39], v[38:39], v[0:1] op_sel_hi:[1,0]
	s_nop 0
	v_pk_mul_f32 v[42:43], v[36:37], v[0:1] op_sel_hi:[1,0]
	v_pk_mul_f32 v[36:37], v[34:35], v[0:1] op_sel_hi:[1,0]
	v_cvt_pk_bf16_f32 v34, v38, v39
	v_cvt_pk_bf16_f32 v35, v40, v41
	v_add_u32_e32 v0, 0xa0, v174
	v_cvt_pk_bf16_f32 v36, v36, v37
	v_cvt_pk_bf16_f32 v37, v42, v43
	global_store_dwordx4 v[50:51], v[34:37], off offset:64
	s_nop 1
	v_mad_i64_i32 v[34:35], s[0:1], v0, s91, v[130:131]
	v_lshl_add_u64 v[34:35], v[34:35], 0, v[132:133]
	v_fmamk_f32 v0, v146, 0x3a800000, v214
	v_cmp_gt_f32_e32 vcc, s90, v0
	v_mul_f32_e32 v36, 0x4b800000, v0
	s_nop 0
	v_cndmask_b32_e32 v0, v0, v36, vcc
	v_rsq_f32_e32 v0, v0
	s_nop 0
	v_mul_f32_e32 v36, 0x45800000, v0
	v_cndmask_b32_e32 v0, v0, v36, vcc
	v_pk_mul_f32 v[32:33], v[32:33], v[0:1] op_sel_hi:[1,0]
	v_pk_mul_f32 v[30:31], v[30:31], v[0:1] op_sel_hi:[1,0]
	v_pk_mul_f32 v[36:37], v[28:29], v[0:1] op_sel_hi:[1,0]
	v_pk_mul_f32 v[28:29], v[26:27], v[0:1] op_sel_hi:[1,0]
	v_cvt_pk_bf16_f32 v26, v30, v31
	v_cvt_pk_bf16_f32 v27, v32, v33
	v_pk_mul_f32 v[24:25], v[24:25], v[0:1] op_sel_hi:[1,0]
	v_cvt_pk_bf16_f32 v28, v28, v29
	v_cvt_pk_bf16_f32 v29, v36, v37
	global_store_dwordx4 v[34:35], v[26:29], off
	v_pk_mul_f32 v[22:23], v[22:23], v[0:1] op_sel_hi:[1,0]
	s_nop 0
	v_pk_mul_f32 v[26:27], v[20:21], v[0:1] op_sel_hi:[1,0]
	v_pk_mul_f32 v[20:21], v[18:19], v[0:1] op_sel_hi:[1,0]
	v_cvt_pk_bf16_f32 v18, v22, v23
	v_cvt_pk_bf16_f32 v19, v24, v25
	v_add_u32_e32 v0, 0xb0, v174
	v_cvt_pk_bf16_f32 v20, v20, v21
	v_cvt_pk_bf16_f32 v21, v26, v27
	global_store_dwordx4 v[34:35], v[18:21], off offset:64
	s_nop 1
	v_mad_i64_i32 v[18:19], s[0:1], v0, s91, v[130:131]
	v_lshl_add_u64 v[136:137], v[18:19], 0, v[132:133]
	v_fmamk_f32 v0, v147, 0x3a800000, v214
	v_cmp_gt_f32_e32 vcc, s90, v0
	v_mul_f32_e32 v18, 0x4b800000, v0
	s_nop 0
	v_cndmask_b32_e32 v0, v0, v18, vcc
	v_rsq_f32_e32 v0, v0
	s_nop 0
	v_mul_f32_e32 v18, 0x45800000, v0
	v_cndmask_b32_e32 v0, v0, v18, vcc
	v_pk_mul_f32 v[18:19], v[12:13], v[0:1] op_sel_hi:[1,0]
	v_pk_mul_f32 v[12:13], v[10:11], v[0:1] op_sel_hi:[1,0]
	v_pk_mul_f32 v[16:17], v[16:17], v[0:1] op_sel_hi:[1,0]
	v_pk_mul_f32 v[14:15], v[14:15], v[0:1] op_sel_hi:[1,0]
	v_pk_mul_f32 v[8:9], v[8:9], v[0:1] op_sel_hi:[1,0]
	v_cvt_pk_bf16_f32 v10, v14, v15
	v_cvt_pk_bf16_f32 v11, v16, v17
	v_cvt_pk_bf16_f32 v12, v12, v13
	v_cvt_pk_bf16_f32 v13, v18, v19
	global_store_dwordx4 v[136:137], v[10:13], off
	v_pk_mul_f32 v[6:7], v[6:7], v[0:1] op_sel_hi:[1,0]
	v_pk_mul_f32 v[4:5], v[4:5], v[0:1] op_sel_hi:[1,0]
	v_pk_mul_f32 v[2:3], v[2:3], v[0:1] op_sel_hi:[1,0]
	v_cvt_pk_bf16_f32 v130, v6, v7
	v_cvt_pk_bf16_f32 v131, v8, v9
	s_nop 0
	v_cvt_pk_bf16_f32 v132, v2, v3
	v_cvt_pk_bf16_f32 v133, v4, v5

.LBB0_205:
	s_andn2_b64 vcc, exec, s[0:1]
	s_cbranch_vccnz .LBB0_207
	s_add_i32 s0, s15, 0xf980
	s_and_b32 s1, s0, 0xffff
	s_mul_i32 s1, s1, 0xba2f
	s_lshr_b32 s4, s1, 23
	s_mul_i32 s1, s4, 0xb0
	s_sub_i32 s0, s0, s1
	s_and_b32 s20, s0, 0xffff
	s_add_i32 s0, s20, 0xffffffa8
	s_min_u32 s0, s0, s20
	s_lshl_b32 s1, s0, 1
	s_and_b32 s1, s1, 0x7fffff8
	s_load_dwordx4 s[16:19], s[48:49], 0x70
	s_cmpk_gt_u32 s20, 0x57
	s_cselect_b32 s5, 4, 0
	s_and_b32 s0, s0, 3
	s_or_b32 s0, s0, s5
	s_or_b32 s5, s0, s1
	s_waitcnt lgkmcnt(0)
	s_add_u32 s0, s16, 0x1000
	s_addc_u32 s1, s17, 0
	s_lshl_b32 s16, s4, 6
	s_lshl_b32 s17, s20, 7
	s_add_u32 s18, s18, s17
	s_addc_u32 s19, s19, 0
	v_lshlrev_b32_e32 v0, 2, v2
	v_lshl_add_u64 v[56:57], s[18:19], 0, v[0:1]
	s_mov_b64 s[18:19], 0x1600000
	v_add_u32_e32 v12, s16, v3
	v_lshl_add_u64 v[66:67], v[56:57], 0, s[18:19]
	s_movk_i32 s17, 0x5800
	v_mad_i64_i32 v[56:57], s[18:19], v12, s17, v[66:67]
	v_add_u32_e32 v0, 2, v12
	global_load_dword v70, v[56:57], off nt
	v_mad_i64_i32 v[56:57], s[18:19], v0, s17, v[66:67]
	v_add_u32_e32 v0, 4, v12
	global_load_dword v71, v[56:57], off nt
	v_mad_i64_i32 v[56:57], s[18:19], v0, s17, v[66:67]
	v_add_u32_e32 v0, 6, v12
	global_load_dword v72, v[56:57], off nt
	v_mad_i64_i32 v[56:57], s[18:19], v0, s17, v[66:67]
	v_add_u32_e32 v0, 8, v12
	global_load_dword v73, v[56:57], off nt
	v_mad_i64_i32 v[56:57], s[18:19], v0, s17, v[66:67]
	v_add_u32_e32 v0, 10, v12
	global_load_dword v74, v[56:57], off nt
	v_mad_i64_i32 v[56:57], s[18:19], v0, s17, v[66:67]
	v_add_u32_e32 v0, 12, v12
	global_load_dword v75, v[56:57], off nt
	v_mad_i64_i32 v[56:57], s[18:19], v0, s17, v[66:67]
	v_add_u32_e32 v0, 14, v12
	global_load_dword v76, v[56:57], off nt
	v_mad_i64_i32 v[56:57], s[18:19], v0, s17, v[66:67]
	v_add_u32_e32 v0, 16, v12
	global_load_dword v77, v[56:57], off nt
	v_mad_i64_i32 v[56:57], s[18:19], v0, s17, v[66:67]
	v_add_u32_e32 v0, 18, v12
	global_load_dword v78, v[56:57], off nt
	v_mad_i64_i32 v[56:57], s[18:19], v0, s17, v[66:67]
	v_add_u32_e32 v0, 20, v12
	global_load_dword v79, v[56:57], off nt
	v_mad_i64_i32 v[56:57], s[18:19], v0, s17, v[66:67]
	v_add_u32_e32 v0, 22, v12
	global_load_dword v80, v[56:57], off nt
	v_mad_i64_i32 v[56:57], s[18:19], v0, s17, v[66:67]
	v_add_u32_e32 v0, 24, v12
	global_load_dword v81, v[56:57], off nt
	v_mad_i64_i32 v[56:57], s[18:19], v0, s17, v[66:67]
	v_add_u32_e32 v0, 26, v12
	global_load_dword v82, v[56:57], off nt
	v_mad_i64_i32 v[56:57], s[18:19], v0, s17, v[66:67]
	v_add_u32_e32 v0, 28, v12
	global_load_dword v83, v[56:57], off nt
	v_mad_i64_i32 v[56:57], s[18:19], v0, s17, v[66:67]
	v_add_u32_e32 v0, 30, v12
	global_load_dword v84, v[56:57], off nt
	v_mad_i64_i32 v[56:57], s[18:19], v0, s17, v[66:67]
	v_add_u32_e32 v0, 32, v12
	global_load_dword v85, v[56:57], off nt
	v_mad_i64_i32 v[56:57], s[18:19], v0, s17, v[66:67]
	v_add_u32_e32 v0, 34, v12
	global_load_dword v86, v[56:57], off nt
	v_mad_i64_i32 v[56:57], s[18:19], v0, s17, v[66:67]
	v_add_u32_e32 v0, 36, v12
	global_load_dword v87, v[56:57], off nt
	v_mad_i64_i32 v[56:57], s[18:19], v0, s17, v[66:67]
	v_add_u32_e32 v0, 38, v12
	global_load_dword v88, v[56:57], off nt
	v_mad_i64_i32 v[56:57], s[18:19], v0, s17, v[66:67]
	v_add_u32_e32 v0, 40, v12
	global_load_dword v89, v[56:57], off nt
	v_mad_i64_i32 v[56:57], s[18:19], v0, s17, v[66:67]
	v_add_u32_e32 v0, 42, v12
	global_load_dword v65, v[56:57], off nt
	v_mad_i64_i32 v[56:57], s[18:19], v0, s17, v[66:67]
	v_add_u32_e32 v0, 44, v12
	global_load_dword v64, v[56:57], off nt
	v_mad_i64_i32 v[56:57], s[18:19], v0, s17, v[66:67]
	v_add_u32_e32 v0, 46, v12
	global_load_dword v63, v[56:57], off nt
	v_mad_i64_i32 v[56:57], s[18:19], v0, s17, v[66:67]
	v_add_u32_e32 v0, 48, v12
	global_load_dword v62, v[56:57], off nt
	v_mad_i64_i32 v[56:57], s[18:19], v0, s17, v[66:67]
	v_add_u32_e32 v0, 50, v12
	global_load_dword v61, v[56:57], off nt
	v_mad_i64_i32 v[56:57], s[18:19], v0, s17, v[66:67]
	v_add_u32_e32 v0, 52, v12
	global_load_dword v60, v[56:57], off nt
	v_mad_i64_i32 v[56:57], s[18:19], v0, s17, v[66:67]
	v_add_u32_e32 v0, 54, v12
	global_load_dword v59, v[56:57], off nt
	v_mad_i64_i32 v[56:57], s[18:19], v0, s17, v[66:67]
	v_add_u32_e32 v0, 56, v12
	global_load_dword v58, v[56:57], off nt
	v_mad_i64_i32 v[56:57], s[18:19], v0, s17, v[66:67]
	v_add_u32_e32 v0, 58, v12
	v_ashrrev_i32_e32 v13, 31, v12
	v_mad_i64_i32 v[68:69], s[18:19], v0, s17, v[66:67]
	v_add_u32_e32 v0, 60, v12
	global_load_dword v57, v[56:57], off nt
	s_lshl_b32 s58, s4, 7
	global_load_dword v56, v[68:69], off nt
	v_mad_i64_i32 v[68:69], s[18:19], v0, s17, v[66:67]
	v_add_u32_e32 v0, 62, v12
	v_lshlrev_b32_e32 v128, 2, v12
	global_load_dword v96, v128, s[0:1]
	v_add_lshl_u32 v128, s16, v21, 2
	global_load_dword v97, v128, s[0:1]
	v_add_lshl_u32 v128, s16, v23, 2
	global_load_dword v98, v128, s[0:1]
	v_add_lshl_u32 v128, s16, v24, 2
	global_load_dword v99, v128, s[0:1]
	v_add_lshl_u32 v128, s16, v25, 2
	global_load_dword v100, v128, s[0:1]
	v_add_lshl_u32 v128, s16, v26, 2
	global_load_dword v101, v128, s[0:1]
	v_add_lshl_u32 v128, s16, v27, 2
	global_load_dword v102, v128, s[0:1]
	v_add_lshl_u32 v128, s16, v28, 2
	global_load_dword v103, v128, s[0:1]
	v_add_lshl_u32 v128, s16, v30, 2
	global_load_dword v104, v128, s[0:1]
	v_add_lshl_u32 v128, s16, v31, 2
	global_load_dword v105, v128, s[0:1]
	v_add_lshl_u32 v128, s16, v32, 2
	global_load_dword v106, v128, s[0:1]
	v_add_lshl_u32 v128, s16, v33, 2
	global_load_dword v107, v128, s[0:1]
	v_add_lshl_u32 v128, s16, v34, 2
	global_load_dword v108, v128, s[0:1]
	v_add_lshl_u32 v128, s16, v35, 2
	global_load_dword v109, v128, s[0:1]
	v_add_lshl_u32 v128, s16, v37, 2
	global_load_dword v110, v128, s[0:1]
	v_add_lshl_u32 v128, s16, v38, 2
	global_load_dword v111, v128, s[0:1]
	v_add_lshl_u32 v128, s16, v39, 2
	global_load_dword v112, v128, s[0:1]
	v_add_lshl_u32 v128, s16, v40, 2
	global_load_dword v113, v128, s[0:1]
	v_add_lshl_u32 v128, s16, v41, 2
	global_load_dword v114, v128, s[0:1]
	v_add_lshl_u32 v128, s16, v42, 2
	global_load_dword v115, v128, s[0:1]
	v_add_lshl_u32 v128, s16, v43, 2
	global_load_dword v116, v128, s[0:1]
	v_add_lshl_u32 v128, s16, v44, 2
	global_load_dword v117, v128, s[0:1]
	v_add_lshl_u32 v128, s16, v45, 2
	global_load_dword v118, v128, s[0:1]
	v_add_lshl_u32 v128, s16, v46, 2
	global_load_dword v119, v128, s[0:1]
	v_add_lshl_u32 v128, s16, v47, 2
	global_load_dword v120, v128, s[0:1]
	v_add_lshl_u32 v128, s16, v48, 2
	global_load_dword v121, v128, s[0:1]
	v_add_lshl_u32 v128, s16, v49, 2
	global_load_dword v122, v128, s[0:1]
	v_add_lshl_u32 v128, s16, v50, 2
	global_load_dword v123, v128, s[0:1]
	v_add_lshl_u32 v128, s16, v51, 2
	global_load_dword v124, v128, s[0:1]
	v_add_lshl_u32 v128, s16, v52, 2
	global_load_dword v125, v128, s[0:1]
	v_add_lshl_u32 v128, s16, v53, 2
	global_load_dword v126, v128, s[0:1]
	v_add_lshl_u32 v128, s16, v54, 2
	global_load_dword v127, v128, s[0:1]
	v_lshl_add_u64 v[12:13], v[12:13], 2, s[0:1]
	v_add_u32_e32 v13, v14, v15
	v_mad_i64_i32 v[66:67], s[18:19], v0, s17, v[66:67]
	global_load_dword v55, v[68:69], off nt
	global_load_dword v0, v[66:67], off nt
	v_add_u32_e32 v67, v14, v22
	s_waitcnt vmcnt(0)
	v_mov_b32_e32 v12, v96
	v_mul_f32_e32 v12, v70, v12
	ds_write_b32 v13, v12
	v_add_u32_e32 v12, s16, v21
	v_ashrrev_i32_e32 v13, 31, v12
	v_lshl_add_u64 v[12:13], v[12:13], 2, s[0:1]
	v_mov_b32_e32 v12, v97
	s_waitcnt vmcnt(0)
	v_mul_f32_e32 v66, v71, v12
	v_add_u32_e32 v12, s16, v23
	v_ashrrev_i32_e32 v13, 31, v12
	v_lshl_add_u64 v[12:13], v[12:13], 2, s[0:1]
	v_mov_b32_e32 v12, v98
	s_waitcnt vmcnt(0)
	v_mul_f32_e32 v12, v72, v12
	ds_write2_b32 v67, v66, v12 offset1:66
	v_add_u32_e32 v12, s16, v24
	v_ashrrev_i32_e32 v13, 31, v12
	v_lshl_add_u64 v[12:13], v[12:13], 2, s[0:1]
	v_mov_b32_e32 v12, v99
	s_waitcnt vmcnt(0)
	v_mul_f32_e32 v66, v73, v12
	v_add_u32_e32 v12, s16, v25
	v_ashrrev_i32_e32 v13, 31, v12
	v_lshl_add_u64 v[12:13], v[12:13], 2, s[0:1]
	v_mov_b32_e32 v12, v100
	s_waitcnt vmcnt(0)
	v_mul_f32_e32 v12, v74, v12
	ds_write2_b32 v67, v66, v12 offset0:132 offset1:198
	v_add_u32_e32 v12, s16, v26
	v_ashrrev_i32_e32 v13, 31, v12
	v_lshl_add_u64 v[12:13], v[12:13], 2, s[0:1]
	v_mov_b32_e32 v12, v101
	s_waitcnt vmcnt(0)
	v_mul_f32_e32 v66, v75, v12
	v_add_u32_e32 v12, s16, v27
	v_ashrrev_i32_e32 v13, 31, v12
	v_lshl_add_u64 v[12:13], v[12:13], 2, s[0:1]
	v_mov_b32_e32 v12, v102
	v_add_u32_e32 v13, 0x400, v67
	v_add_u32_e32 v67, v14, v29
	s_waitcnt vmcnt(0)
	v_mul_f32_e32 v12, v76, v12
	ds_write2_b32 v13, v66, v12 offset0:8 offset1:74
	v_add_u32_e32 v12, s16, v28
	v_ashrrev_i32_e32 v13, 31, v12
	v_lshl_add_u64 v[12:13], v[12:13], 2, s[0:1]
	v_mov_b32_e32 v12, v103
	s_waitcnt vmcnt(0)
	v_mul_f32_e32 v66, v77, v12
	v_add_u32_e32 v12, s16, v30
	v_ashrrev_i32_e32 v13, 31, v12
	v_lshl_add_u64 v[12:13], v[12:13], 2, s[0:1]
	v_mov_b32_e32 v12, v104
	s_waitcnt vmcnt(0)
	v_mul_f32_e32 v12, v78, v12
	ds_write2_b32 v67, v66, v12 offset1:66
	v_add_u32_e32 v12, s16, v31
	v_ashrrev_i32_e32 v13, 31, v12
	v_lshl_add_u64 v[12:13], v[12:13], 2, s[0:1]
	v_mov_b32_e32 v12, v105
	s_waitcnt vmcnt(0)
	v_mul_f32_e32 v66, v79, v12
	v_add_u32_e32 v12, s16, v32
	v_ashrrev_i32_e32 v13, 31, v12
	v_lshl_add_u64 v[12:13], v[12:13], 2, s[0:1]
	v_mov_b32_e32 v12, v106
	s_waitcnt vmcnt(0)
	v_mul_f32_e32 v12, v80, v12
	ds_write2_b32 v67, v66, v12 offset0:132 offset1:198
	v_add_u32_e32 v12, s16, v33
	v_ashrrev_i32_e32 v13, 31, v12
	v_lshl_add_u64 v[12:13], v[12:13], 2, s[0:1]
	v_mov_b32_e32 v12, v107
	s_waitcnt vmcnt(0)
	v_mul_f32_e32 v66, v81, v12
	v_add_u32_e32 v12, s16, v34
	v_ashrrev_i32_e32 v13, 31, v12
	v_lshl_add_u64 v[12:13], v[12:13], 2, s[0:1]
	v_mov_b32_e32 v12, v108
	v_add_u32_e32 v13, 0x400, v67
	s_waitcnt vmcnt(0)
	v_mul_f32_e32 v12, v82, v12
	ds_write2_b32 v13, v66, v12 offset0:8 offset1:74
	v_add_u32_e32 v12, s16, v35
	v_add_u32_e32 v66, s16, v37
	v_ashrrev_i32_e32 v13, 31, v12
	v_ashrrev_i32_e32 v67, 31, v66
	v_lshl_add_u64 v[12:13], v[12:13], 2, s[0:1]
	v_lshl_add_u64 v[66:67], v[66:67], 2, s[0:1]
	v_mov_b32_e32 v12, v109
	s_nop 0
	v_mov_b32_e32 v66, v110
	s_waitcnt vmcnt(1)
	v_mul_f32_e32 v13, v83, v12
	v_add_u32_e32 v12, v14, v36
	s_waitcnt vmcnt(0)
	v_mul_f32_e32 v66, v84, v66
	ds_write2_b32 v12, v13, v66 offset1:66
	v_add_u32_e32 v66, s16, v38
	v_ashrrev_i32_e32 v67, 31, v66
	v_lshl_add_u64 v[66:67], v[66:67], 2, s[0:1]
	v_mov_b32_e32 v13, v111
	v_add_u32_e32 v66, s16, v39
	v_ashrrev_i32_e32 v67, 31, v66
	v_lshl_add_u64 v[66:67], v[66:67], 2, s[0:1]
	v_mov_b32_e32 v66, v112
	v_add_u32_e32 v68, 0x400, v12
	s_waitcnt vmcnt(1)
	v_mul_f32_e32 v13, v85, v13
	s_waitcnt vmcnt(0)
	v_mul_f32_e32 v66, v86, v66
	ds_write2_b32 v12, v13, v66 offset0:132 offset1:198
	v_add_u32_e32 v66, s16, v40
	v_ashrrev_i32_e32 v67, 31, v66
	v_lshl_add_u64 v[66:67], v[66:67], 2, s[0:1]
	v_mov_b32_e32 v13, v113
	v_add_u32_e32 v66, s16, v41
	v_ashrrev_i32_e32 v67, 31, v66
	v_lshl_add_u64 v[66:67], v[66:67], 2, s[0:1]
	v_mov_b32_e32 v66, v114
	s_waitcnt vmcnt(1)
	v_mul_f32_e32 v13, v87, v13
	s_waitcnt vmcnt(0)
	v_mul_f32_e32 v66, v88, v66
	ds_write2_b32 v68, v13, v66 offset0:8 offset1:74
	v_add_u32_e32 v66, s16, v42
	v_ashrrev_i32_e32 v67, 31, v66
	v_lshl_add_u64 v[66:67], v[66:67], 2, s[0:1]
	v_mov_b32_e32 v13, v115
	v_add_u32_e32 v66, s16, v43
	v_ashrrev_i32_e32 v67, 31, v66
	v_lshl_add_u64 v[66:67], v[66:67], 2, s[0:1]
	v_mov_b32_e32 v66, v116
	s_waitcnt vmcnt(1)
	v_mul_f32_e32 v13, v89, v13
	s_waitcnt vmcnt(0)
	v_mul_f32_e32 v65, v65, v66
	v_add_u32_e32 v66, s16, v44
	v_ashrrev_i32_e32 v67, 31, v66
	v_lshl_add_u64 v[66:67], v[66:67], 2, s[0:1]
	ds_write2_b32 v68, v13, v65 offset0:140 offset1:206
	v_mov_b32_e32 v13, v117
	v_add_u32_e32 v66, 0x800, v12
	s_waitcnt vmcnt(0)
	v_mul_f32_e32 v13, v64, v13
	v_add_u32_e32 v64, s16, v45
	v_ashrrev_i32_e32 v65, 31, v64
	v_lshl_add_u64 v[64:65], v[64:65], 2, s[0:1]
	v_mov_b32_e32 v64, v118
	s_waitcnt vmcnt(0)
	v_mul_f32_e32 v63, v63, v64
	v_add_u32_e32 v64, s16, v46
	v_ashrrev_i32_e32 v65, 31, v64
	v_lshl_add_u64 v[64:65], v[64:65], 2, s[0:1]
	ds_write2_b32 v66, v13, v63 offset0:16 offset1:82
	v_mov_b32_e32 v13, v119
	s_waitcnt vmcnt(0)
	v_mul_f32_e32 v13, v62, v13
	v_add_u32_e32 v62, s16, v47
	v_ashrrev_i32_e32 v63, 31, v62
	v_lshl_add_u64 v[62:63], v[62:63], 2, s[0:1]
	v_mov_b32_e32 v62, v120
	s_waitcnt vmcnt(0)
	v_mul_f32_e32 v61, v61, v62
	v_add_u32_e32 v62, s16, v48
	v_ashrrev_i32_e32 v63, 31, v62
	v_lshl_add_u64 v[62:63], v[62:63], 2, s[0:1]
	ds_write2_b32 v66, v13, v61 offset0:148 offset1:214
	v_mov_b32_e32 v13, v121
	v_add_u32_e32 v62, 0xc00, v12
	s_waitcnt vmcnt(0)
	v_mul_f32_e32 v13, v60, v13
	v_add_u32_e32 v60, s16, v49
	v_ashrrev_i32_e32 v61, 31, v60
	v_lshl_add_u64 v[60:61], v[60:61], 2, s[0:1]
	v_mov_b32_e32 v60, v122
	s_waitcnt vmcnt(0)
	v_mul_f32_e32 v59, v59, v60
	v_add_u32_e32 v60, s16, v50
	v_ashrrev_i32_e32 v61, 31, v60
	v_lshl_add_u64 v[60:61], v[60:61], 2, s[0:1]
	ds_write2_b32 v62, v13, v59 offset0:24 offset1:90
	v_mov_b32_e32 v13, v123
	s_waitcnt vmcnt(0)
	v_mul_f32_e32 v13, v58, v13
	v_add_u32_e32 v58, s16, v51
	v_ashrrev_i32_e32 v59, 31, v58
	v_lshl_add_u64 v[58:59], v[58:59], 2, s[0:1]
	v_mov_b32_e32 v58, v124
	s_waitcnt vmcnt(0)
	v_mul_f32_e32 v57, v57, v58
	v_add_u32_e32 v58, s16, v52
	v_ashrrev_i32_e32 v59, 31, v58
	v_lshl_add_u64 v[58:59], v[58:59], 2, s[0:1]
	ds_write2_b32 v62, v13, v57 offset0:156 offset1:222
	v_mov_b32_e32 v13, v125
	s_waitcnt vmcnt(0)
	v_mul_f32_e32 v13, v56, v13
	v_add_u32_e32 v56, s16, v53
	v_ashrrev_i32_e32 v57, 31, v56
	v_lshl_add_u64 v[56:57], v[56:57], 2, s[0:1]
	v_mov_b32_e32 v56, v126
	s_waitcnt vmcnt(0)
	v_mul_f32_e32 v55, v55, v56
	v_add_u32_e32 v56, 0x1000, v12
	ds_write2_b32 v56, v13, v55 offset0:32 offset1:98
	v_add_u32_e32 v56, s16, v54
	v_ashrrev_i32_e32 v57, 31, v56
	v_lshl_add_u64 v[56:57], v[56:57], 2, s[0:1]
	v_mov_b32_e32 v13, v127
	s_mov_b32 s1, 0xffff0000
	s_lshl_b32 s0, s5, 5
	v_add_u32_e32 v76, s0, v16
	v_ashrrev_i32_e32 v77, 31, v76
	v_lshlrev_b64 v[76:77], 11, v[76:77]
	s_waitcnt vmcnt(0)
	v_mul_f32_e32 v0, v0, v13
	ds_write_b32 v12, v0 offset:4752
	s_waitcnt lgkmcnt(0)
	ds_read2_b32 v[60:61], v17 offset0:33 offset1:41
	ds_read2_b32 v[62:63], v17 offset1:8
	ds_read2_b32 v[64:65], v17 offset0:66 offset1:74
	ds_read2_b32 v[66:67], v17 offset0:99 offset1:107
	ds_read2_b32 v[68:69], v17 offset0:132 offset1:140
	ds_read2_b32 v[70:71], v17 offset0:165 offset1:173
	ds_read2_b32 v[72:73], v17 offset0:198 offset1:206
	ds_read2_b32 v[74:75], v17 offset0:231 offset1:239
	s_waitcnt lgkmcnt(7)
	v_bfe_u32 v55, v60, 16, 1
	s_waitcnt lgkmcnt(6)
	v_bfe_u32 v0, v62, 16, 1
	v_add3_u32 v0, v62, v0, s92
	v_lshrrev_b32_e32 v0, 16, v0
	v_add3_u32 v55, v60, v55, s92
	v_and_or_b32 v56, v55, s1, v0
	s_waitcnt lgkmcnt(5)
	v_bfe_u32 v0, v64, 16, 1
	v_add3_u32 v0, v64, v0, s92
	s_waitcnt lgkmcnt(4)
	v_bfe_u32 v55, v66, 16, 1
	v_lshrrev_b32_e32 v0, 16, v0
	v_add3_u32 v55, v66, v55, s92
	v_and_or_b32 v57, v55, s1, v0
	s_waitcnt lgkmcnt(3)
	v_bfe_u32 v0, v68, 16, 1
	v_add3_u32 v0, v68, v0, s92
	s_waitcnt lgkmcnt(2)
	v_bfe_u32 v55, v70, 16, 1
	v_lshrrev_b32_e32 v0, 16, v0
	v_add3_u32 v55, v70, v55, s92
	v_and_or_b32 v58, v55, s1, v0
	s_waitcnt lgkmcnt(1)
	v_bfe_u32 v0, v72, 16, 1
	v_add3_u32 v0, v72, v0, s92
	s_waitcnt lgkmcnt(0)
	v_bfe_u32 v55, v74, 16, 1
	v_lshrrev_b32_e32 v0, 16, v0
	v_add3_u32 v55, v74, v55, s92
	v_and_or_b32 v59, v55, s1, v0
	v_bfe_u32 v0, v63, 16, 1
	v_lshl_add_u64 v[12:13], v[6:7], 0, s[58:59]
	v_add3_u32 v0, v63, v0, s92
	v_bfe_u32 v55, v61, 16, 1
	v_lshl_add_u64 v[76:77], v[12:13], 0, v[76:77]
	v_lshrrev_b32_e32 v0, 16, v0
	v_add3_u32 v55, v61, v55, s92
	global_store_dwordx4 v[76:77], v[56:59], off
	v_add_u32_e32 v60, s0, v18
	v_ashrrev_i32_e32 v61, 31, v60
	v_and_or_b32 v56, v55, s1, v0
	v_bfe_u32 v0, v65, 16, 1
	v_add3_u32 v0, v65, v0, s92
	v_bfe_u32 v55, v67, 16, 1
	v_lshrrev_b32_e32 v0, 16, v0
	v_add3_u32 v55, v67, v55, s92
	v_and_or_b32 v57, v55, s1, v0
	v_bfe_u32 v0, v69, 16, 1
	v_add3_u32 v0, v69, v0, s92
	v_bfe_u32 v55, v71, 16, 1
	v_lshrrev_b32_e32 v0, 16, v0
	v_add3_u32 v55, v71, v55, s92
	v_and_or_b32 v58, v55, s1, v0
	v_bfe_u32 v0, v73, 16, 1
	v_add3_u32 v0, v73, v0, s92
	v_bfe_u32 v55, v75, 16, 1
	v_lshrrev_b32_e32 v0, 16, v0
	v_add3_u32 v55, v75, v55, s92
	v_lshlrev_b64 v[60:61], 11, v[60:61]
	v_and_or_b32 v59, v55, s1, v0
	v_lshl_add_u64 v[60:61], v[12:13], 0, v[60:61]
	global_store_dwordx4 v[60:61], v[56:59], off
	ds_read2_b32 v[60:61], v17 offset0:49 offset1:57
	ds_read2_b32 v[62:63], v17 offset0:16 offset1:24
	ds_read2_b32 v[64:65], v17 offset0:82 offset1:90
	ds_read2_b32 v[66:67], v17 offset0:115 offset1:123
	ds_read2_b32 v[68:69], v17 offset0:148 offset1:156
	ds_read2_b32 v[70:71], v17 offset0:181 offset1:189
	ds_read2_b32 v[72:73], v17 offset0:214 offset1:222
	ds_read2_b32 v[74:75], v17 offset0:247 offset1:255
	s_waitcnt lgkmcnt(7)
	v_bfe_u32 v55, v60, 16, 1
	s_waitcnt lgkmcnt(6)
	v_bfe_u32 v0, v62, 16, 1
	v_add3_u32 v0, v62, v0, s92
	v_lshrrev_b32_e32 v0, 16, v0
	v_add3_u32 v55, v60, v55, s92
	v_and_or_b32 v56, v55, s1, v0
	s_waitcnt lgkmcnt(5)
	v_bfe_u32 v0, v64, 16, 1
	v_add3_u32 v0, v64, v0, s92
	s_waitcnt lgkmcnt(4)
	v_bfe_u32 v55, v66, 16, 1
	v_lshrrev_b32_e32 v0, 16, v0
	v_add3_u32 v55, v66, v55, s92
	v_and_or_b32 v57, v55, s1, v0
	s_waitcnt lgkmcnt(3)
	v_bfe_u32 v0, v68, 16, 1
	v_add3_u32 v0, v68, v0, s92
	s_waitcnt lgkmcnt(2)
	v_bfe_u32 v55, v70, 16, 1
	v_lshrrev_b32_e32 v0, 16, v0
	v_add3_u32 v55, v70, v55, s92
	v_and_or_b32 v58, v55, s1, v0
	s_waitcnt lgkmcnt(1)
	v_bfe_u32 v0, v72, 16, 1
	v_add3_u32 v0, v72, v0, s92
	s_waitcnt lgkmcnt(0)
	v_bfe_u32 v55, v74, 16, 1
	v_lshrrev_b32_e32 v0, 16, v0
	v_add3_u32 v55, v74, v55, s92
	v_add_u32_e32 v76, s0, v19
	v_and_or_b32 v59, v55, s1, v0
	v_ashrrev_i32_e32 v77, 31, v76
	v_bfe_u32 v0, v63, 16, 1
	v_lshlrev_b64 v[76:77], 11, v[76:77]
	v_add3_u32 v0, v63, v0, s92
	v_bfe_u32 v55, v61, 16, 1
	v_lshl_add_u64 v[76:77], v[12:13], 0, v[76:77]
	v_lshrrev_b32_e32 v0, 16, v0
	v_add3_u32 v55, v61, v55, s92
	global_store_dwordx4 v[76:77], v[56:59], off
	v_add_u32_e32 v60, s0, v20
	v_ashrrev_i32_e32 v61, 31, v60
	v_and_or_b32 v56, v55, s1, v0
	v_bfe_u32 v0, v65, 16, 1
	v_add3_u32 v0, v65, v0, s92
	v_bfe_u32 v55, v67, 16, 1
	v_lshrrev_b32_e32 v0, 16, v0
	v_add3_u32 v55, v67, v55, s92
	v_and_or_b32 v57, v55, s1, v0
	v_bfe_u32 v0, v69, 16, 1
	v_add3_u32 v0, v69, v0, s92
	v_bfe_u32 v55, v71, 16, 1
	v_lshrrev_b32_e32 v0, 16, v0
	v_add3_u32 v55, v71, v55, s92
	v_and_or_b32 v58, v55, s1, v0
	v_bfe_u32 v0, v73, 16, 1
	v_add3_u32 v0, v73, v0, s92
	v_bfe_u32 v55, v75, 16, 1
	v_lshrrev_b32_e32 v0, 16, v0
	v_add3_u32 v55, v75, v55, s92
	v_lshlrev_b64 v[60:61], 11, v[60:61]
	v_and_or_b32 v59, v55, s1, v0
	v_lshl_add_u64 v[12:13], v[12:13], 0, v[60:61]
	global_store_dwordx4 v[12:13], v[56:59], off
	s_waitcnt lgkmcnt(0)

.LBB0_211:
	s_andn2_b64 vcc, exec, s[0:1]
	s_cbranch_vccnz .LBB0_200
	s_mul_hi_i32 s0, s15, 0x38e38e39
	s_lshr_b32 s1, s0, 31
	s_ashr_i32 s0, s0, 4
	s_add_i32 s20, s0, s1
	s_mul_i32 s0, s20, 0xffffffb8
	s_load_dwordx4 s[16:19], s[48:49], 0x8
	s_add_i32 s0, s15, s0
	s_bfe_u32 s1, s0, 0x20001
	s_and_b32 s0, s0, 0x7fffff8
	s_and_b32 s4, s6, 4
	s_or_b32 s0, s4, s0
	s_or_b32 s1, s0, s1
	s_waitcnt lgkmcnt(0)
	s_add_u32 s4, s16, 0x1000
	s_addc_u32 s5, s17, 0
	s_lshl_b32 s0, s20, 6
	s_mulk_i32 s20, 0xf700
	s_add_i32 s16, s9, s20
	s_ashr_i32 s17, s16, 31
	s_lshl_b64 s[16:17], s[16:17], 2
	s_add_u32 s16, s18, s16
	s_addc_u32 s17, s19, s17
	v_lshlrev_b32_e32 v0, 2, v2
	v_lshl_add_u64 v[56:57], s[16:17], 0, v[0:1]
	s_mov_b64 s[16:17], 0x900000
	v_add_u32_e32 v12, s0, v3
	v_lshl_add_u64 v[66:67], v[56:57], 0, s[16:17]
	v_mad_i64_i32 v[56:57], s[16:17], v12, s95, v[66:67]
	v_add_u32_e32 v0, 2, v12
	global_load_dword v70, v[56:57], off nt
	v_mad_i64_i32 v[56:57], s[16:17], v0, s95, v[66:67]
	v_add_u32_e32 v0, 4, v12
	global_load_dword v71, v[56:57], off nt
	v_mad_i64_i32 v[56:57], s[16:17], v0, s95, v[66:67]
	v_add_u32_e32 v0, 6, v12
	global_load_dword v72, v[56:57], off nt
	v_mad_i64_i32 v[56:57], s[16:17], v0, s95, v[66:67]
	v_add_u32_e32 v0, 8, v12
	global_load_dword v73, v[56:57], off nt
	v_mad_i64_i32 v[56:57], s[16:17], v0, s95, v[66:67]
	v_add_u32_e32 v0, 10, v12
	global_load_dword v74, v[56:57], off nt
	v_mad_i64_i32 v[56:57], s[16:17], v0, s95, v[66:67]
	v_add_u32_e32 v0, 12, v12
	global_load_dword v75, v[56:57], off nt
	v_mad_i64_i32 v[56:57], s[16:17], v0, s95, v[66:67]
	v_add_u32_e32 v0, 14, v12
	global_load_dword v76, v[56:57], off nt
	v_mad_i64_i32 v[56:57], s[16:17], v0, s95, v[66:67]
	v_add_u32_e32 v0, 16, v12
	global_load_dword v77, v[56:57], off nt
	v_mad_i64_i32 v[56:57], s[16:17], v0, s95, v[66:67]
	v_add_u32_e32 v0, 18, v12
	global_load_dword v78, v[56:57], off nt
	v_mad_i64_i32 v[56:57], s[16:17], v0, s95, v[66:67]
	v_add_u32_e32 v0, 20, v12
	global_load_dword v79, v[56:57], off nt
	v_mad_i64_i32 v[56:57], s[16:17], v0, s95, v[66:67]
	v_add_u32_e32 v0, 22, v12
	global_load_dword v80, v[56:57], off nt
	v_mad_i64_i32 v[56:57], s[16:17], v0, s95, v[66:67]
	v_add_u32_e32 v0, 24, v12
	global_load_dword v81, v[56:57], off nt
	v_mad_i64_i32 v[56:57], s[16:17], v0, s95, v[66:67]
	v_add_u32_e32 v0, 26, v12
	global_load_dword v82, v[56:57], off nt
	v_mad_i64_i32 v[56:57], s[16:17], v0, s95, v[66:67]
	v_add_u32_e32 v0, 28, v12
	global_load_dword v83, v[56:57], off nt
	v_mad_i64_i32 v[56:57], s[16:17], v0, s95, v[66:67]
	v_add_u32_e32 v0, 30, v12
	global_load_dword v84, v[56:57], off nt
	v_mad_i64_i32 v[56:57], s[16:17], v0, s95, v[66:67]
	v_add_u32_e32 v0, 32, v12
	global_load_dword v85, v[56:57], off nt
	v_mad_i64_i32 v[56:57], s[16:17], v0, s95, v[66:67]
	v_add_u32_e32 v0, 34, v12
	global_load_dword v86, v[56:57], off nt
	v_mad_i64_i32 v[56:57], s[16:17], v0, s95, v[66:67]
	v_add_u32_e32 v0, 36, v12
	global_load_dword v87, v[56:57], off nt
	v_mad_i64_i32 v[56:57], s[16:17], v0, s95, v[66:67]
	v_add_u32_e32 v0, 38, v12
	global_load_dword v88, v[56:57], off nt
	v_mad_i64_i32 v[56:57], s[16:17], v0, s95, v[66:67]
	v_add_u32_e32 v0, 40, v12
	global_load_dword v89, v[56:57], off nt
	v_mad_i64_i32 v[56:57], s[16:17], v0, s95, v[66:67]
	v_add_u32_e32 v0, 42, v12
	global_load_dword v65, v[56:57], off nt
	v_mad_i64_i32 v[56:57], s[16:17], v0, s95, v[66:67]
	v_add_u32_e32 v0, 44, v12
	global_load_dword v64, v[56:57], off nt
	v_mad_i64_i32 v[56:57], s[16:17], v0, s95, v[66:67]
	v_add_u32_e32 v0, 46, v12
	global_load_dword v63, v[56:57], off nt
	v_mad_i64_i32 v[56:57], s[16:17], v0, s95, v[66:67]
	v_add_u32_e32 v0, 48, v12
	global_load_dword v62, v[56:57], off nt
	v_mad_i64_i32 v[56:57], s[16:17], v0, s95, v[66:67]
	v_add_u32_e32 v0, 50, v12
	global_load_dword v61, v[56:57], off nt
	v_mad_i64_i32 v[56:57], s[16:17], v0, s95, v[66:67]
	v_add_u32_e32 v0, 52, v12
	global_load_dword v60, v[56:57], off nt
	v_mad_i64_i32 v[56:57], s[16:17], v0, s95, v[66:67]
	v_add_u32_e32 v0, 54, v12
	global_load_dword v59, v[56:57], off nt
	v_mad_i64_i32 v[56:57], s[16:17], v0, s95, v[66:67]
	v_add_u32_e32 v0, 56, v12
	global_load_dword v58, v[56:57], off nt
	v_mad_i64_i32 v[56:57], s[16:17], v0, s95, v[66:67]
	v_add_u32_e32 v0, 58, v12
	v_ashrrev_i32_e32 v13, 31, v12
	v_mad_i64_i32 v[68:69], s[16:17], v0, s95, v[66:67]
	v_add_u32_e32 v0, 60, v12
	global_load_dword v57, v[56:57], off nt
	s_nop 0
	global_load_dword v56, v[68:69], off nt
	v_mad_i64_i32 v[68:69], s[16:17], v0, s95, v[66:67]
	v_add_u32_e32 v0, 62, v12
	v_lshlrev_b32_e32 v128, 2, v12
	global_load_dword v96, v128, s[4:5]
	v_add_lshl_u32 v128, s0, v21, 2
	global_load_dword v97, v128, s[4:5]
	v_add_lshl_u32 v128, s0, v23, 2
	global_load_dword v98, v128, s[4:5]
	v_add_lshl_u32 v128, s0, v24, 2
	global_load_dword v99, v128, s[4:5]
	v_add_lshl_u32 v128, s0, v25, 2
	global_load_dword v100, v128, s[4:5]
	v_add_lshl_u32 v128, s0, v26, 2
	global_load_dword v101, v128, s[4:5]
	v_add_lshl_u32 v128, s0, v27, 2
	global_load_dword v102, v128, s[4:5]
	v_add_lshl_u32 v128, s0, v28, 2
	global_load_dword v103, v128, s[4:5]
	v_add_lshl_u32 v128, s0, v30, 2
	global_load_dword v104, v128, s[4:5]
	v_add_lshl_u32 v128, s0, v31, 2
	global_load_dword v105, v128, s[4:5]
	v_add_lshl_u32 v128, s0, v32, 2
	global_load_dword v106, v128, s[4:5]
	v_add_lshl_u32 v128, s0, v33, 2
	global_load_dword v107, v128, s[4:5]
	v_add_lshl_u32 v128, s0, v34, 2
	global_load_dword v108, v128, s[4:5]
	v_add_lshl_u32 v128, s0, v35, 2
	global_load_dword v109, v128, s[4:5]
	v_add_lshl_u32 v128, s0, v37, 2
	global_load_dword v110, v128, s[4:5]
	v_add_lshl_u32 v128, s0, v38, 2
	global_load_dword v111, v128, s[4:5]
	v_add_lshl_u32 v128, s0, v39, 2
	global_load_dword v112, v128, s[4:5]
	v_add_lshl_u32 v128, s0, v40, 2
	global_load_dword v113, v128, s[4:5]
	v_add_lshl_u32 v128, s0, v41, 2
	global_load_dword v114, v128, s[4:5]
	v_add_lshl_u32 v128, s0, v42, 2
	global_load_dword v115, v128, s[4:5]
	v_add_lshl_u32 v128, s0, v43, 2
	global_load_dword v116, v128, s[4:5]
	v_add_lshl_u32 v128, s0, v44, 2
	global_load_dword v117, v128, s[4:5]
	v_add_lshl_u32 v128, s0, v45, 2
	global_load_dword v118, v128, s[4:5]
	v_add_lshl_u32 v128, s0, v46, 2
	global_load_dword v119, v128, s[4:5]
	v_add_lshl_u32 v128, s0, v47, 2
	global_load_dword v120, v128, s[4:5]
	v_add_lshl_u32 v128, s0, v48, 2
	global_load_dword v121, v128, s[4:5]
	v_add_lshl_u32 v128, s0, v49, 2
	global_load_dword v122, v128, s[4:5]
	v_add_lshl_u32 v128, s0, v50, 2
	global_load_dword v123, v128, s[4:5]
	v_add_lshl_u32 v128, s0, v51, 2
	global_load_dword v124, v128, s[4:5]
	v_add_lshl_u32 v128, s0, v52, 2
	global_load_dword v125, v128, s[4:5]
	v_add_lshl_u32 v128, s0, v53, 2
	global_load_dword v126, v128, s[4:5]
	v_add_lshl_u32 v128, s0, v54, 2
	global_load_dword v127, v128, s[4:5]
	v_lshl_add_u64 v[12:13], v[12:13], 2, s[4:5]
	v_add_u32_e32 v13, v14, v15
	v_mad_i64_i32 v[66:67], s[16:17], v0, s95, v[66:67]
	global_load_dword v55, v[68:69], off nt
	global_load_dword v0, v[66:67], off nt
	v_add_u32_e32 v67, v14, v22
	s_waitcnt vmcnt(0)
	v_mov_b32_e32 v12, v96
	v_mul_f32_e32 v12, v70, v12
	ds_write_b32 v13, v12
	v_add_u32_e32 v12, s0, v21
	v_ashrrev_i32_e32 v13, 31, v12
	v_lshl_add_u64 v[12:13], v[12:13], 2, s[4:5]
	v_mov_b32_e32 v12, v97
	s_waitcnt vmcnt(0)
	v_mul_f32_e32 v66, v71, v12
	v_add_u32_e32 v12, s0, v23
	v_ashrrev_i32_e32 v13, 31, v12
	v_lshl_add_u64 v[12:13], v[12:13], 2, s[4:5]
	v_mov_b32_e32 v12, v98
	s_waitcnt vmcnt(0)
	v_mul_f32_e32 v12, v72, v12
	ds_write2_b32 v67, v66, v12 offset1:66
	v_add_u32_e32 v12, s0, v24
	v_ashrrev_i32_e32 v13, 31, v12
	v_lshl_add_u64 v[12:13], v[12:13], 2, s[4:5]
	v_mov_b32_e32 v12, v99
	s_waitcnt vmcnt(0)
	v_mul_f32_e32 v66, v73, v12
	v_add_u32_e32 v12, s0, v25
	v_ashrrev_i32_e32 v13, 31, v12
	v_lshl_add_u64 v[12:13], v[12:13], 2, s[4:5]
	v_mov_b32_e32 v12, v100
	s_waitcnt vmcnt(0)
	v_mul_f32_e32 v12, v74, v12
	ds_write2_b32 v67, v66, v12 offset0:132 offset1:198
	v_add_u32_e32 v12, s0, v26
	v_ashrrev_i32_e32 v13, 31, v12
	v_lshl_add_u64 v[12:13], v[12:13], 2, s[4:5]
	v_mov_b32_e32 v12, v101
	s_waitcnt vmcnt(0)
	v_mul_f32_e32 v66, v75, v12
	v_add_u32_e32 v12, s0, v27
	v_ashrrev_i32_e32 v13, 31, v12
	v_lshl_add_u64 v[12:13], v[12:13], 2, s[4:5]
	v_mov_b32_e32 v12, v102
	v_add_u32_e32 v13, 0x400, v67
	v_add_u32_e32 v67, v14, v29
	s_waitcnt vmcnt(0)
	v_mul_f32_e32 v12, v76, v12
	ds_write2_b32 v13, v66, v12 offset0:8 offset1:74
	v_add_u32_e32 v12, s0, v28
	v_ashrrev_i32_e32 v13, 31, v12
	v_lshl_add_u64 v[12:13], v[12:13], 2, s[4:5]
	v_mov_b32_e32 v12, v103
	s_waitcnt vmcnt(0)
	v_mul_f32_e32 v66, v77, v12
	v_add_u32_e32 v12, s0, v30
	v_ashrrev_i32_e32 v13, 31, v12
	v_lshl_add_u64 v[12:13], v[12:13], 2, s[4:5]
	v_mov_b32_e32 v12, v104
	s_waitcnt vmcnt(0)
	v_mul_f32_e32 v12, v78, v12
	ds_write2_b32 v67, v66, v12 offset1:66
	v_add_u32_e32 v12, s0, v31
	v_ashrrev_i32_e32 v13, 31, v12
	v_lshl_add_u64 v[12:13], v[12:13], 2, s[4:5]
	v_mov_b32_e32 v12, v105
	s_waitcnt vmcnt(0)
	v_mul_f32_e32 v66, v79, v12
	v_add_u32_e32 v12, s0, v32
	v_ashrrev_i32_e32 v13, 31, v12
	v_lshl_add_u64 v[12:13], v[12:13], 2, s[4:5]
	v_mov_b32_e32 v12, v106
	s_waitcnt vmcnt(0)
	v_mul_f32_e32 v12, v80, v12
	ds_write2_b32 v67, v66, v12 offset0:132 offset1:198
	v_add_u32_e32 v12, s0, v33
	v_ashrrev_i32_e32 v13, 31, v12
	v_lshl_add_u64 v[12:13], v[12:13], 2, s[4:5]
	v_mov_b32_e32 v12, v107
	s_waitcnt vmcnt(0)
	v_mul_f32_e32 v66, v81, v12
	v_add_u32_e32 v12, s0, v34
	v_ashrrev_i32_e32 v13, 31, v12
	v_lshl_add_u64 v[12:13], v[12:13], 2, s[4:5]
	v_mov_b32_e32 v12, v108
	v_add_u32_e32 v13, 0x400, v67
	s_waitcnt vmcnt(0)
	v_mul_f32_e32 v12, v82, v12
	ds_write2_b32 v13, v66, v12 offset0:8 offset1:74
	v_add_u32_e32 v12, s0, v35
	v_add_u32_e32 v66, s0, v37
	v_ashrrev_i32_e32 v13, 31, v12
	v_ashrrev_i32_e32 v67, 31, v66
	v_lshl_add_u64 v[12:13], v[12:13], 2, s[4:5]
	v_lshl_add_u64 v[66:67], v[66:67], 2, s[4:5]
	v_mov_b32_e32 v12, v109
	s_nop 0
	v_mov_b32_e32 v66, v110
	s_waitcnt vmcnt(1)
	v_mul_f32_e32 v13, v83, v12
	v_add_u32_e32 v12, v14, v36
	s_waitcnt vmcnt(0)
	v_mul_f32_e32 v66, v84, v66
	ds_write2_b32 v12, v13, v66 offset1:66
	v_add_u32_e32 v66, s0, v38
	v_ashrrev_i32_e32 v67, 31, v66
	v_lshl_add_u64 v[66:67], v[66:67], 2, s[4:5]
	v_mov_b32_e32 v13, v111
	v_add_u32_e32 v66, s0, v39
	v_ashrrev_i32_e32 v67, 31, v66
	v_lshl_add_u64 v[66:67], v[66:67], 2, s[4:5]
	v_mov_b32_e32 v66, v112
	v_add_u32_e32 v68, 0x400, v12
	s_waitcnt vmcnt(1)
	v_mul_f32_e32 v13, v85, v13
	s_waitcnt vmcnt(0)
	v_mul_f32_e32 v66, v86, v66
	ds_write2_b32 v12, v13, v66 offset0:132 offset1:198
	v_add_u32_e32 v66, s0, v40
	v_ashrrev_i32_e32 v67, 31, v66
	v_lshl_add_u64 v[66:67], v[66:67], 2, s[4:5]
	v_mov_b32_e32 v13, v113
	v_add_u32_e32 v66, s0, v41
	v_ashrrev_i32_e32 v67, 31, v66
	v_lshl_add_u64 v[66:67], v[66:67], 2, s[4:5]
	v_mov_b32_e32 v66, v114
	s_waitcnt vmcnt(1)
	v_mul_f32_e32 v13, v87, v13
	s_waitcnt vmcnt(0)
	v_mul_f32_e32 v66, v88, v66
	ds_write2_b32 v68, v13, v66 offset0:8 offset1:74
	v_add_u32_e32 v66, s0, v42
	v_ashrrev_i32_e32 v67, 31, v66
	v_lshl_add_u64 v[66:67], v[66:67], 2, s[4:5]
	v_mov_b32_e32 v13, v115
	v_add_u32_e32 v66, s0, v43
	v_ashrrev_i32_e32 v67, 31, v66
	v_lshl_add_u64 v[66:67], v[66:67], 2, s[4:5]
	v_mov_b32_e32 v66, v116
	s_waitcnt vmcnt(1)
	v_mul_f32_e32 v13, v89, v13
	s_waitcnt vmcnt(0)
	v_mul_f32_e32 v65, v65, v66
	v_add_u32_e32 v66, s0, v44
	v_ashrrev_i32_e32 v67, 31, v66
	v_lshl_add_u64 v[66:67], v[66:67], 2, s[4:5]
	ds_write2_b32 v68, v13, v65 offset0:140 offset1:206
	v_mov_b32_e32 v13, v117
	v_add_u32_e32 v66, 0x800, v12
	s_waitcnt vmcnt(0)
	v_mul_f32_e32 v13, v64, v13
	v_add_u32_e32 v64, s0, v45
	v_ashrrev_i32_e32 v65, 31, v64
	v_lshl_add_u64 v[64:65], v[64:65], 2, s[4:5]
	v_mov_b32_e32 v64, v118
	s_waitcnt vmcnt(0)
	v_mul_f32_e32 v63, v63, v64
	v_add_u32_e32 v64, s0, v46
	v_ashrrev_i32_e32 v65, 31, v64
	v_lshl_add_u64 v[64:65], v[64:65], 2, s[4:5]
	ds_write2_b32 v66, v13, v63 offset0:16 offset1:82
	v_mov_b32_e32 v13, v119
	s_waitcnt vmcnt(0)
	v_mul_f32_e32 v13, v62, v13
	v_add_u32_e32 v62, s0, v47
	v_ashrrev_i32_e32 v63, 31, v62
	v_lshl_add_u64 v[62:63], v[62:63], 2, s[4:5]
	v_mov_b32_e32 v62, v120
	s_waitcnt vmcnt(0)
	v_mul_f32_e32 v61, v61, v62
	v_add_u32_e32 v62, s0, v48
	v_ashrrev_i32_e32 v63, 31, v62
	v_lshl_add_u64 v[62:63], v[62:63], 2, s[4:5]
	ds_write2_b32 v66, v13, v61 offset0:148 offset1:214
	v_mov_b32_e32 v13, v121
	v_add_u32_e32 v62, 0xc00, v12
	s_waitcnt vmcnt(0)
	v_mul_f32_e32 v13, v60, v13
	v_add_u32_e32 v60, s0, v49
	v_ashrrev_i32_e32 v61, 31, v60
	v_lshl_add_u64 v[60:61], v[60:61], 2, s[4:5]
	v_mov_b32_e32 v60, v122
	s_waitcnt vmcnt(0)
	v_mul_f32_e32 v59, v59, v60
	v_add_u32_e32 v60, s0, v50
	v_ashrrev_i32_e32 v61, 31, v60
	v_lshl_add_u64 v[60:61], v[60:61], 2, s[4:5]
	ds_write2_b32 v62, v13, v59 offset0:24 offset1:90
	v_mov_b32_e32 v13, v123
	s_waitcnt vmcnt(0)
	v_mul_f32_e32 v13, v58, v13
	v_add_u32_e32 v58, s0, v51
	v_ashrrev_i32_e32 v59, 31, v58
	v_lshl_add_u64 v[58:59], v[58:59], 2, s[4:5]
	v_mov_b32_e32 v58, v124
	s_waitcnt vmcnt(0)
	v_mul_f32_e32 v57, v57, v58
	v_add_u32_e32 v58, s0, v52
	v_ashrrev_i32_e32 v59, 31, v58
	v_lshl_add_u64 v[58:59], v[58:59], 2, s[4:5]
	ds_write2_b32 v62, v13, v57 offset0:156 offset1:222
	v_mov_b32_e32 v13, v125
	s_waitcnt vmcnt(0)
	v_mul_f32_e32 v13, v56, v13
	v_add_u32_e32 v56, s0, v53
	v_ashrrev_i32_e32 v57, 31, v56
	v_lshl_add_u64 v[56:57], v[56:57], 2, s[4:5]
	v_mov_b32_e32 v56, v126
	s_waitcnt vmcnt(0)
	v_mul_f32_e32 v55, v55, v56
	v_add_u32_e32 v56, 0x1000, v12
	ds_write2_b32 v56, v13, v55 offset0:32 offset1:98
	v_add_u32_e32 v56, s0, v54
	v_ashrrev_i32_e32 v57, 31, v56
	v_lshl_add_u64 v[56:57], v[56:57], 2, s[4:5]
	v_mov_b32_e32 v13, v127
	s_lshl_b32 s4, s1, 5
	s_ashr_i32 s1, s0, 31
	v_add_u32_e32 v76, s4, v16
	v_ashrrev_i32_e32 v77, 31, v76
	v_lshlrev_b64 v[76:77], 11, v[76:77]
	s_waitcnt vmcnt(0)
	v_mul_f32_e32 v0, v0, v13
	ds_write_b32 v12, v0 offset:4752
	s_waitcnt lgkmcnt(0)
	ds_read2_b32 v[60:61], v17 offset0:33 offset1:41
	ds_read2_b32 v[62:63], v17 offset1:8
	ds_read2_b32 v[64:65], v17 offset0:66 offset1:74
	ds_read2_b32 v[66:67], v17 offset0:99 offset1:107
	v_lshl_add_u64 v[12:13], s[0:1], 1, v[10:11]
	s_mov_b32 s0, 0xffff0000
	s_waitcnt lgkmcnt(3)
	v_bfe_u32 v55, v60, 16, 1
	s_waitcnt lgkmcnt(2)
	v_bfe_u32 v0, v62, 16, 1
	v_add3_u32 v0, v62, v0, s92
	v_lshrrev_b32_e32 v0, 16, v0
	v_add3_u32 v55, v60, v55, s92
	ds_read2_b32 v[68:69], v17 offset0:132 offset1:140
	ds_read2_b32 v[70:71], v17 offset0:165 offset1:173
	v_and_or_b32 v56, v55, s0, v0
	s_waitcnt lgkmcnt(3)
	v_bfe_u32 v0, v64, 16, 1
	v_add3_u32 v0, v64, v0, s92
	s_waitcnt lgkmcnt(2)
	v_bfe_u32 v55, v66, 16, 1
	v_lshrrev_b32_e32 v0, 16, v0
	v_add3_u32 v55, v66, v55, s92
	ds_read2_b32 v[72:73], v17 offset0:198 offset1:206
	ds_read2_b32 v[74:75], v17 offset0:231 offset1:239
	v_and_or_b32 v57, v55, s0, v0
	s_waitcnt lgkmcnt(3)
	v_bfe_u32 v0, v68, 16, 1
	v_add3_u32 v0, v68, v0, s92
	s_waitcnt lgkmcnt(2)
	v_bfe_u32 v55, v70, 16, 1
	v_lshrrev_b32_e32 v0, 16, v0
	v_add3_u32 v55, v70, v55, s92
	v_and_or_b32 v58, v55, s0, v0
	s_waitcnt lgkmcnt(1)
	v_bfe_u32 v0, v72, 16, 1
	v_add3_u32 v0, v72, v0, s92
	s_waitcnt lgkmcnt(0)
	v_bfe_u32 v55, v74, 16, 1
	v_lshrrev_b32_e32 v0, 16, v0
	v_add3_u32 v55, v74, v55, s92
	v_and_or_b32 v59, v55, s0, v0
	v_bfe_u32 v0, v63, 16, 1
	v_add3_u32 v0, v63, v0, s92
	v_bfe_u32 v55, v61, 16, 1
	v_lshl_add_u64 v[76:77], v[12:13], 0, v[76:77]
	v_lshrrev_b32_e32 v0, 16, v0
	v_add3_u32 v55, v61, v55, s92
	global_store_dwordx4 v[76:77], v[56:59], off
	v_add_u32_e32 v60, s4, v18
	v_ashrrev_i32_e32 v61, 31, v60
	v_and_or_b32 v56, v55, s0, v0
	v_bfe_u32 v0, v65, 16, 1
	v_add3_u32 v0, v65, v0, s92
	v_bfe_u32 v55, v67, 16, 1
	v_lshrrev_b32_e32 v0, 16, v0
	v_add3_u32 v55, v67, v55, s92
	v_and_or_b32 v57, v55, s0, v0
	v_bfe_u32 v0, v69, 16, 1
	v_add3_u32 v0, v69, v0, s92
	v_bfe_u32 v55, v71, 16, 1
	v_lshrrev_b32_e32 v0, 16, v0
	v_add3_u32 v55, v71, v55, s92
	v_and_or_b32 v58, v55, s0, v0
	v_bfe_u32 v0, v73, 16, 1
	v_add3_u32 v0, v73, v0, s92
	v_bfe_u32 v55, v75, 16, 1
	v_lshrrev_b32_e32 v0, 16, v0
	v_add3_u32 v55, v75, v55, s92
	v_lshlrev_b64 v[60:61], 11, v[60:61]
	v_and_or_b32 v59, v55, s0, v0
	v_lshl_add_u64 v[60:61], v[12:13], 0, v[60:61]
	global_store_dwordx4 v[60:61], v[56:59], off
	ds_read2_b32 v[60:61], v17 offset0:49 offset1:57
	ds_read2_b32 v[62:63], v17 offset0:16 offset1:24
	ds_read2_b32 v[64:65], v17 offset0:82 offset1:90
	ds_read2_b32 v[66:67], v17 offset0:115 offset1:123
	ds_read2_b32 v[68:69], v17 offset0:148 offset1:156
	ds_read2_b32 v[70:71], v17 offset0:181 offset1:189
	ds_read2_b32 v[72:73], v17 offset0:214 offset1:222
	ds_read2_b32 v[74:75], v17 offset0:247 offset1:255
	s_waitcnt lgkmcnt(7)
	v_bfe_u32 v55, v60, 16, 1
	s_waitcnt lgkmcnt(6)
	v_bfe_u32 v0, v62, 16, 1
	v_add3_u32 v0, v62, v0, s92
	v_lshrrev_b32_e32 v0, 16, v0
	v_add3_u32 v55, v60, v55, s92
	v_and_or_b32 v56, v55, s0, v0
	s_waitcnt lgkmcnt(5)
	v_bfe_u32 v0, v64, 16, 1
	v_add3_u32 v0, v64, v0, s92
	s_waitcnt lgkmcnt(4)
	v_bfe_u32 v55, v66, 16, 1
	v_lshrrev_b32_e32 v0, 16, v0
	v_add3_u32 v55, v66, v55, s92
	v_and_or_b32 v57, v55, s0, v0
	s_waitcnt lgkmcnt(3)
	v_bfe_u32 v0, v68, 16, 1
	v_add3_u32 v0, v68, v0, s92
	s_waitcnt lgkmcnt(2)
	v_bfe_u32 v55, v70, 16, 1
	v_lshrrev_b32_e32 v0, 16, v0
	v_add3_u32 v55, v70, v55, s92
	v_and_or_b32 v58, v55, s0, v0
	s_waitcnt lgkmcnt(1)
	v_bfe_u32 v0, v72, 16, 1
	v_add3_u32 v0, v72, v0, s92
	s_waitcnt lgkmcnt(0)
	v_bfe_u32 v55, v74, 16, 1
	v_lshrrev_b32_e32 v0, 16, v0
	v_add3_u32 v55, v74, v55, s92
	v_add_u32_e32 v76, s4, v19
	v_and_or_b32 v59, v55, s0, v0
	v_ashrrev_i32_e32 v77, 31, v76
	v_bfe_u32 v0, v63, 16, 1
	v_lshlrev_b64 v[76:77], 11, v[76:77]
	v_add3_u32 v0, v63, v0, s92
	v_bfe_u32 v55, v61, 16, 1
	v_lshl_add_u64 v[76:77], v[12:13], 0, v[76:77]
	v_lshrrev_b32_e32 v0, 16, v0
	v_add3_u32 v55, v61, v55, s92
	global_store_dwordx4 v[76:77], v[56:59], off
	v_add_u32_e32 v60, s4, v20
	v_ashrrev_i32_e32 v61, 31, v60
	v_and_or_b32 v56, v55, s0, v0
	v_bfe_u32 v0, v65, 16, 1
	v_add3_u32 v0, v65, v0, s92
	v_bfe_u32 v55, v67, 16, 1
	v_lshrrev_b32_e32 v0, 16, v0
	v_add3_u32 v55, v67, v55, s92
	v_and_or_b32 v57, v55, s0, v0
	v_bfe_u32 v0, v69, 16, 1
	v_add3_u32 v0, v69, v0, s92
	v_bfe_u32 v55, v71, 16, 1
	v_lshrrev_b32_e32 v0, 16, v0
	v_add3_u32 v55, v71, v55, s92
	v_and_or_b32 v58, v55, s0, v0
	v_bfe_u32 v0, v73, 16, 1
	v_add3_u32 v0, v73, v0, s92
	v_bfe_u32 v55, v75, 16, 1
	v_lshrrev_b32_e32 v0, 16, v0
	v_add3_u32 v55, v75, v55, s92
	v_lshlrev_b64 v[60:61], 11, v[60:61]
	v_and_or_b32 v59, v55, s0, v0
	v_lshl_add_u64 v[12:13], v[12:13], 0, v[60:61]
	global_store_dwordx4 v[12:13], v[56:59], off
	s_waitcnt lgkmcnt(0)
	s_branch .LBB0_200

.LBB0_302:
	s_andn2_b64 vcc, exec, s[0:1]
	s_cbranch_vccnz .LBB0_304
	s_add_i32 s0, s13, 0xf980
	s_and_b32 s1, s0, 0xffff
	s_mul_i32 s1, s1, 0xba2f
	s_lshr_b32 s4, s1, 23
	s_mul_i32 s1, s4, 0xb0
	s_sub_i32 s0, s0, s1
	s_and_b32 s15, s0, 0xffff
	s_add_i32 s0, s15, 0xffffffa8
	s_min_u32 s0, s0, s15
	s_lshl_b32 s1, s0, 1
	s_and_b32 s1, s1, 0x7fffff8
	s_load_dwordx4 s[16:19], s[48:49], 0x70
	s_cmpk_gt_u32 s15, 0x57
	s_cselect_b32 s5, 4, 0
	s_and_b32 s0, s0, 3
	s_or_b32 s0, s0, s5
	s_or_b32 s5, s0, s1
	s_waitcnt lgkmcnt(0)
	s_add_u32 s0, s16, 0x1000
	s_addc_u32 s1, s17, 0
	s_lshl_b32 s14, s4, 6
	s_lshl_b32 s15, s15, 7
	s_add_u32 s16, s18, s15
	s_addc_u32 s17, s19, 0
	v_lshlrev_b32_e32 v0, 2, v2
	v_lshl_add_u64 v[56:57], s[16:17], 0, v[0:1]
	s_mov_b64 s[16:17], 0x1600000
	v_add_u32_e32 v12, s14, v3
	v_lshl_add_u64 v[66:67], v[56:57], 0, s[16:17]
	s_movk_i32 s15, 0x5800
	v_mad_i64_i32 v[56:57], s[16:17], v12, s15, v[66:67]
	v_add_u32_e32 v0, 2, v12
	global_load_dword v70, v[56:57], off nt
	v_mad_i64_i32 v[56:57], s[16:17], v0, s15, v[66:67]
	v_add_u32_e32 v0, 4, v12
	global_load_dword v71, v[56:57], off nt
	v_mad_i64_i32 v[56:57], s[16:17], v0, s15, v[66:67]
	v_add_u32_e32 v0, 6, v12
	global_load_dword v72, v[56:57], off nt
	v_mad_i64_i32 v[56:57], s[16:17], v0, s15, v[66:67]
	v_add_u32_e32 v0, 8, v12
	global_load_dword v73, v[56:57], off nt
	v_mad_i64_i32 v[56:57], s[16:17], v0, s15, v[66:67]
	v_add_u32_e32 v0, 10, v12
	global_load_dword v74, v[56:57], off nt
	v_mad_i64_i32 v[56:57], s[16:17], v0, s15, v[66:67]
	v_add_u32_e32 v0, 12, v12
	global_load_dword v75, v[56:57], off nt
	v_mad_i64_i32 v[56:57], s[16:17], v0, s15, v[66:67]
	v_add_u32_e32 v0, 14, v12
	global_load_dword v76, v[56:57], off nt
	v_mad_i64_i32 v[56:57], s[16:17], v0, s15, v[66:67]
	v_add_u32_e32 v0, 16, v12
	global_load_dword v77, v[56:57], off nt
	v_mad_i64_i32 v[56:57], s[16:17], v0, s15, v[66:67]
	v_add_u32_e32 v0, 18, v12
	global_load_dword v78, v[56:57], off nt
	v_mad_i64_i32 v[56:57], s[16:17], v0, s15, v[66:67]
	v_add_u32_e32 v0, 20, v12
	global_load_dword v79, v[56:57], off nt
	v_mad_i64_i32 v[56:57], s[16:17], v0, s15, v[66:67]
	v_add_u32_e32 v0, 22, v12
	global_load_dword v80, v[56:57], off nt
	v_mad_i64_i32 v[56:57], s[16:17], v0, s15, v[66:67]
	v_add_u32_e32 v0, 24, v12
	global_load_dword v81, v[56:57], off nt
	v_mad_i64_i32 v[56:57], s[16:17], v0, s15, v[66:67]
	v_add_u32_e32 v0, 26, v12
	global_load_dword v82, v[56:57], off nt
	v_mad_i64_i32 v[56:57], s[16:17], v0, s15, v[66:67]
	v_add_u32_e32 v0, 28, v12
	global_load_dword v83, v[56:57], off nt
	v_mad_i64_i32 v[56:57], s[16:17], v0, s15, v[66:67]
	v_add_u32_e32 v0, 30, v12
	global_load_dword v84, v[56:57], off nt
	v_mad_i64_i32 v[56:57], s[16:17], v0, s15, v[66:67]
	v_add_u32_e32 v0, 32, v12
	global_load_dword v85, v[56:57], off nt
	v_mad_i64_i32 v[56:57], s[16:17], v0, s15, v[66:67]
	v_add_u32_e32 v0, 34, v12
	global_load_dword v86, v[56:57], off nt
	v_mad_i64_i32 v[56:57], s[16:17], v0, s15, v[66:67]
	v_add_u32_e32 v0, 36, v12
	global_load_dword v87, v[56:57], off nt
	v_mad_i64_i32 v[56:57], s[16:17], v0, s15, v[66:67]
	v_add_u32_e32 v0, 38, v12
	global_load_dword v88, v[56:57], off nt
	v_mad_i64_i32 v[56:57], s[16:17], v0, s15, v[66:67]
	v_add_u32_e32 v0, 40, v12
	global_load_dword v89, v[56:57], off nt
	v_mad_i64_i32 v[56:57], s[16:17], v0, s15, v[66:67]
	v_add_u32_e32 v0, 42, v12
	global_load_dword v65, v[56:57], off nt
	v_mad_i64_i32 v[56:57], s[16:17], v0, s15, v[66:67]
	v_add_u32_e32 v0, 44, v12
	global_load_dword v64, v[56:57], off nt
	v_mad_i64_i32 v[56:57], s[16:17], v0, s15, v[66:67]
	v_add_u32_e32 v0, 46, v12
	global_load_dword v63, v[56:57], off nt
	v_mad_i64_i32 v[56:57], s[16:17], v0, s15, v[66:67]
	v_add_u32_e32 v0, 48, v12
	global_load_dword v62, v[56:57], off nt
	v_mad_i64_i32 v[56:57], s[16:17], v0, s15, v[66:67]
	v_add_u32_e32 v0, 50, v12
	global_load_dword v61, v[56:57], off nt
	v_mad_i64_i32 v[56:57], s[16:17], v0, s15, v[66:67]
	v_add_u32_e32 v0, 52, v12
	global_load_dword v60, v[56:57], off nt
	v_mad_i64_i32 v[56:57], s[16:17], v0, s15, v[66:67]
	v_add_u32_e32 v0, 54, v12
	global_load_dword v59, v[56:57], off nt
	v_mad_i64_i32 v[56:57], s[16:17], v0, s15, v[66:67]
	v_add_u32_e32 v0, 56, v12
	global_load_dword v58, v[56:57], off nt
	v_mad_i64_i32 v[56:57], s[16:17], v0, s15, v[66:67]
	v_add_u32_e32 v0, 58, v12
	v_ashrrev_i32_e32 v13, 31, v12
	v_mad_i64_i32 v[68:69], s[16:17], v0, s15, v[66:67]
	v_add_u32_e32 v0, 60, v12
	global_load_dword v57, v[56:57], off nt
	s_lshl_b32 s58, s4, 7
	global_load_dword v56, v[68:69], off nt
	v_mad_i64_i32 v[68:69], s[16:17], v0, s15, v[66:67]
	v_add_u32_e32 v0, 62, v12
	v_lshlrev_b32_e32 v128, 2, v12
	global_load_dword v96, v128, s[0:1]
	v_add_lshl_u32 v128, s14, v21, 2
	global_load_dword v97, v128, s[0:1]
	v_add_lshl_u32 v128, s14, v23, 2
	global_load_dword v98, v128, s[0:1]
	v_add_lshl_u32 v128, s14, v24, 2
	global_load_dword v99, v128, s[0:1]
	v_add_lshl_u32 v128, s14, v25, 2
	global_load_dword v100, v128, s[0:1]
	v_add_lshl_u32 v128, s14, v26, 2
	global_load_dword v101, v128, s[0:1]
	v_add_lshl_u32 v128, s14, v27, 2
	global_load_dword v102, v128, s[0:1]
	v_add_lshl_u32 v128, s14, v28, 2
	global_load_dword v103, v128, s[0:1]
	v_add_lshl_u32 v128, s14, v30, 2
	global_load_dword v104, v128, s[0:1]
	v_add_lshl_u32 v128, s14, v31, 2
	global_load_dword v105, v128, s[0:1]
	v_add_lshl_u32 v128, s14, v32, 2
	global_load_dword v106, v128, s[0:1]
	v_add_lshl_u32 v128, s14, v33, 2
	global_load_dword v107, v128, s[0:1]
	v_add_lshl_u32 v128, s14, v34, 2
	global_load_dword v108, v128, s[0:1]
	v_add_lshl_u32 v128, s14, v35, 2
	global_load_dword v109, v128, s[0:1]
	v_add_lshl_u32 v128, s14, v37, 2
	global_load_dword v110, v128, s[0:1]
	v_add_lshl_u32 v128, s14, v38, 2
	global_load_dword v111, v128, s[0:1]
	v_add_lshl_u32 v128, s14, v39, 2
	global_load_dword v112, v128, s[0:1]
	v_add_lshl_u32 v128, s14, v40, 2
	global_load_dword v113, v128, s[0:1]
	v_add_lshl_u32 v128, s14, v41, 2
	global_load_dword v114, v128, s[0:1]
	v_add_lshl_u32 v128, s14, v42, 2
	global_load_dword v115, v128, s[0:1]
	v_add_lshl_u32 v128, s14, v43, 2
	global_load_dword v116, v128, s[0:1]
	v_add_lshl_u32 v128, s14, v44, 2
	global_load_dword v117, v128, s[0:1]
	v_add_lshl_u32 v128, s14, v45, 2
	global_load_dword v118, v128, s[0:1]
	v_add_lshl_u32 v128, s14, v46, 2
	global_load_dword v119, v128, s[0:1]
	v_add_lshl_u32 v128, s14, v47, 2
	global_load_dword v120, v128, s[0:1]
	v_add_lshl_u32 v128, s14, v48, 2
	global_load_dword v121, v128, s[0:1]
	v_add_lshl_u32 v128, s14, v49, 2
	global_load_dword v122, v128, s[0:1]
	v_add_lshl_u32 v128, s14, v50, 2
	global_load_dword v123, v128, s[0:1]
	v_add_lshl_u32 v128, s14, v51, 2
	global_load_dword v124, v128, s[0:1]
	v_add_lshl_u32 v128, s14, v52, 2
	global_load_dword v125, v128, s[0:1]
	v_add_lshl_u32 v128, s14, v53, 2
	global_load_dword v126, v128, s[0:1]
	v_add_lshl_u32 v128, s14, v54, 2
	global_load_dword v127, v128, s[0:1]
	v_lshl_add_u64 v[12:13], v[12:13], 2, s[0:1]
	v_add_u32_e32 v13, v14, v15
	v_mad_i64_i32 v[66:67], s[16:17], v0, s15, v[66:67]
	global_load_dword v55, v[68:69], off nt
	global_load_dword v0, v[66:67], off nt
	v_add_u32_e32 v67, v14, v22
	s_waitcnt vmcnt(0)
	v_mov_b32_e32 v12, v96
	v_mul_f32_e32 v12, v70, v12
	ds_write_b32 v13, v12
	v_add_u32_e32 v12, s14, v21
	v_ashrrev_i32_e32 v13, 31, v12
	v_lshl_add_u64 v[12:13], v[12:13], 2, s[0:1]
	v_mov_b32_e32 v12, v97
	s_waitcnt vmcnt(0)
	v_mul_f32_e32 v66, v71, v12
	v_add_u32_e32 v12, s14, v23
	v_ashrrev_i32_e32 v13, 31, v12
	v_lshl_add_u64 v[12:13], v[12:13], 2, s[0:1]
	v_mov_b32_e32 v12, v98
	s_waitcnt vmcnt(0)
	v_mul_f32_e32 v12, v72, v12
	ds_write2_b32 v67, v66, v12 offset1:66
	v_add_u32_e32 v12, s14, v24
	v_ashrrev_i32_e32 v13, 31, v12
	v_lshl_add_u64 v[12:13], v[12:13], 2, s[0:1]
	v_mov_b32_e32 v12, v99
	s_waitcnt vmcnt(0)
	v_mul_f32_e32 v66, v73, v12
	v_add_u32_e32 v12, s14, v25
	v_ashrrev_i32_e32 v13, 31, v12
	v_lshl_add_u64 v[12:13], v[12:13], 2, s[0:1]
	v_mov_b32_e32 v12, v100
	s_waitcnt vmcnt(0)
	v_mul_f32_e32 v12, v74, v12
	ds_write2_b32 v67, v66, v12 offset0:132 offset1:198
	v_add_u32_e32 v12, s14, v26
	v_ashrrev_i32_e32 v13, 31, v12
	v_lshl_add_u64 v[12:13], v[12:13], 2, s[0:1]
	v_mov_b32_e32 v12, v101
	s_waitcnt vmcnt(0)
	v_mul_f32_e32 v66, v75, v12
	v_add_u32_e32 v12, s14, v27
	v_ashrrev_i32_e32 v13, 31, v12
	v_lshl_add_u64 v[12:13], v[12:13], 2, s[0:1]
	v_mov_b32_e32 v12, v102
	v_add_u32_e32 v13, 0x400, v67
	v_add_u32_e32 v67, v14, v29
	s_waitcnt vmcnt(0)
	v_mul_f32_e32 v12, v76, v12
	ds_write2_b32 v13, v66, v12 offset0:8 offset1:74
	v_add_u32_e32 v12, s14, v28
	v_ashrrev_i32_e32 v13, 31, v12
	v_lshl_add_u64 v[12:13], v[12:13], 2, s[0:1]
	v_mov_b32_e32 v12, v103
	s_waitcnt vmcnt(0)
	v_mul_f32_e32 v66, v77, v12
	v_add_u32_e32 v12, s14, v30
	v_ashrrev_i32_e32 v13, 31, v12
	v_lshl_add_u64 v[12:13], v[12:13], 2, s[0:1]
	v_mov_b32_e32 v12, v104
	s_waitcnt vmcnt(0)
	v_mul_f32_e32 v12, v78, v12
	ds_write2_b32 v67, v66, v12 offset1:66
	v_add_u32_e32 v12, s14, v31
	v_ashrrev_i32_e32 v13, 31, v12
	v_lshl_add_u64 v[12:13], v[12:13], 2, s[0:1]
	v_mov_b32_e32 v12, v105
	s_waitcnt vmcnt(0)
	v_mul_f32_e32 v66, v79, v12
	v_add_u32_e32 v12, s14, v32
	v_ashrrev_i32_e32 v13, 31, v12
	v_lshl_add_u64 v[12:13], v[12:13], 2, s[0:1]
	v_mov_b32_e32 v12, v106
	s_waitcnt vmcnt(0)
	v_mul_f32_e32 v12, v80, v12
	ds_write2_b32 v67, v66, v12 offset0:132 offset1:198
	v_add_u32_e32 v12, s14, v33
	v_ashrrev_i32_e32 v13, 31, v12
	v_lshl_add_u64 v[12:13], v[12:13], 2, s[0:1]
	v_mov_b32_e32 v12, v107
	s_waitcnt vmcnt(0)
	v_mul_f32_e32 v66, v81, v12
	v_add_u32_e32 v12, s14, v34
	v_ashrrev_i32_e32 v13, 31, v12
	v_lshl_add_u64 v[12:13], v[12:13], 2, s[0:1]
	v_mov_b32_e32 v12, v108
	v_add_u32_e32 v13, 0x400, v67
	s_waitcnt vmcnt(0)
	v_mul_f32_e32 v12, v82, v12
	ds_write2_b32 v13, v66, v12 offset0:8 offset1:74
	v_add_u32_e32 v12, s14, v35
	v_add_u32_e32 v66, s14, v37
	v_ashrrev_i32_e32 v13, 31, v12
	v_ashrrev_i32_e32 v67, 31, v66
	v_lshl_add_u64 v[12:13], v[12:13], 2, s[0:1]
	v_lshl_add_u64 v[66:67], v[66:67], 2, s[0:1]
	v_mov_b32_e32 v12, v109
	s_nop 0
	v_mov_b32_e32 v66, v110
	s_waitcnt vmcnt(1)
	v_mul_f32_e32 v13, v83, v12
	v_add_u32_e32 v12, v14, v36
	s_waitcnt vmcnt(0)
	v_mul_f32_e32 v66, v84, v66
	ds_write2_b32 v12, v13, v66 offset1:66
	v_add_u32_e32 v66, s14, v38
	v_ashrrev_i32_e32 v67, 31, v66
	v_lshl_add_u64 v[66:67], v[66:67], 2, s[0:1]
	v_mov_b32_e32 v13, v111
	v_add_u32_e32 v66, s14, v39
	v_ashrrev_i32_e32 v67, 31, v66
	v_lshl_add_u64 v[66:67], v[66:67], 2, s[0:1]
	v_mov_b32_e32 v66, v112
	v_add_u32_e32 v68, 0x400, v12
	s_waitcnt vmcnt(1)
	v_mul_f32_e32 v13, v85, v13
	s_waitcnt vmcnt(0)
	v_mul_f32_e32 v66, v86, v66
	ds_write2_b32 v12, v13, v66 offset0:132 offset1:198
	v_add_u32_e32 v66, s14, v40
	v_ashrrev_i32_e32 v67, 31, v66
	v_lshl_add_u64 v[66:67], v[66:67], 2, s[0:1]
	v_mov_b32_e32 v13, v113
	v_add_u32_e32 v66, s14, v41
	v_ashrrev_i32_e32 v67, 31, v66
	v_lshl_add_u64 v[66:67], v[66:67], 2, s[0:1]
	v_mov_b32_e32 v66, v114
	s_waitcnt vmcnt(1)
	v_mul_f32_e32 v13, v87, v13
	s_waitcnt vmcnt(0)
	v_mul_f32_e32 v66, v88, v66
	ds_write2_b32 v68, v13, v66 offset0:8 offset1:74
	v_add_u32_e32 v66, s14, v42
	v_ashrrev_i32_e32 v67, 31, v66
	v_lshl_add_u64 v[66:67], v[66:67], 2, s[0:1]
	v_mov_b32_e32 v13, v115
	v_add_u32_e32 v66, s14, v43
	v_ashrrev_i32_e32 v67, 31, v66
	v_lshl_add_u64 v[66:67], v[66:67], 2, s[0:1]
	v_mov_b32_e32 v66, v116
	s_waitcnt vmcnt(1)
	v_mul_f32_e32 v13, v89, v13
	s_waitcnt vmcnt(0)
	v_mul_f32_e32 v65, v65, v66
	v_add_u32_e32 v66, s14, v44
	v_ashrrev_i32_e32 v67, 31, v66
	v_lshl_add_u64 v[66:67], v[66:67], 2, s[0:1]
	ds_write2_b32 v68, v13, v65 offset0:140 offset1:206
	v_mov_b32_e32 v13, v117
	v_add_u32_e32 v66, 0x800, v12
	s_waitcnt vmcnt(0)
	v_mul_f32_e32 v13, v64, v13
	v_add_u32_e32 v64, s14, v45
	v_ashrrev_i32_e32 v65, 31, v64
	v_lshl_add_u64 v[64:65], v[64:65], 2, s[0:1]
	v_mov_b32_e32 v64, v118
	s_waitcnt vmcnt(0)
	v_mul_f32_e32 v63, v63, v64
	v_add_u32_e32 v64, s14, v46
	v_ashrrev_i32_e32 v65, 31, v64
	v_lshl_add_u64 v[64:65], v[64:65], 2, s[0:1]
	ds_write2_b32 v66, v13, v63 offset0:16 offset1:82
	v_mov_b32_e32 v13, v119
	s_waitcnt vmcnt(0)
	v_mul_f32_e32 v13, v62, v13
	v_add_u32_e32 v62, s14, v47
	v_ashrrev_i32_e32 v63, 31, v62
	v_lshl_add_u64 v[62:63], v[62:63], 2, s[0:1]
	v_mov_b32_e32 v62, v120
	s_waitcnt vmcnt(0)
	v_mul_f32_e32 v61, v61, v62
	v_add_u32_e32 v62, s14, v48
	v_ashrrev_i32_e32 v63, 31, v62
	v_lshl_add_u64 v[62:63], v[62:63], 2, s[0:1]
	ds_write2_b32 v66, v13, v61 offset0:148 offset1:214
	v_mov_b32_e32 v13, v121
	v_add_u32_e32 v62, 0xc00, v12
	s_waitcnt vmcnt(0)
	v_mul_f32_e32 v13, v60, v13
	v_add_u32_e32 v60, s14, v49
	v_ashrrev_i32_e32 v61, 31, v60
	v_lshl_add_u64 v[60:61], v[60:61], 2, s[0:1]
	v_mov_b32_e32 v60, v122
	s_waitcnt vmcnt(0)
	v_mul_f32_e32 v59, v59, v60
	v_add_u32_e32 v60, s14, v50
	v_ashrrev_i32_e32 v61, 31, v60
	v_lshl_add_u64 v[60:61], v[60:61], 2, s[0:1]
	ds_write2_b32 v62, v13, v59 offset0:24 offset1:90
	v_mov_b32_e32 v13, v123
	s_waitcnt vmcnt(0)
	v_mul_f32_e32 v13, v58, v13
	v_add_u32_e32 v58, s14, v51
	v_ashrrev_i32_e32 v59, 31, v58
	v_lshl_add_u64 v[58:59], v[58:59], 2, s[0:1]
	v_mov_b32_e32 v58, v124
	s_waitcnt vmcnt(0)
	v_mul_f32_e32 v57, v57, v58
	v_add_u32_e32 v58, s14, v52
	v_ashrrev_i32_e32 v59, 31, v58
	v_lshl_add_u64 v[58:59], v[58:59], 2, s[0:1]
	ds_write2_b32 v62, v13, v57 offset0:156 offset1:222
	v_mov_b32_e32 v13, v125
	s_waitcnt vmcnt(0)
	v_mul_f32_e32 v13, v56, v13
	v_add_u32_e32 v56, s14, v53
	v_ashrrev_i32_e32 v57, 31, v56
	v_lshl_add_u64 v[56:57], v[56:57], 2, s[0:1]
	v_mov_b32_e32 v56, v126
	s_waitcnt vmcnt(0)
	v_mul_f32_e32 v55, v55, v56
	v_add_u32_e32 v56, 0x1000, v12
	ds_write2_b32 v56, v13, v55 offset0:32 offset1:98
	v_add_u32_e32 v56, s14, v54
	v_ashrrev_i32_e32 v57, 31, v56
	v_lshl_add_u64 v[56:57], v[56:57], 2, s[0:1]
	v_mov_b32_e32 v13, v127
	s_mov_b32 s1, 0xffff0000
	s_lshl_b32 s0, s5, 5
	v_add_u32_e32 v76, s0, v16
	v_ashrrev_i32_e32 v77, 31, v76
	v_lshlrev_b64 v[76:77], 11, v[76:77]
	s_waitcnt vmcnt(0)
	v_mul_f32_e32 v0, v0, v13
	ds_write_b32 v12, v0 offset:4752
	s_waitcnt lgkmcnt(0)
	ds_read2_b32 v[60:61], v17 offset0:33 offset1:41
	ds_read2_b32 v[62:63], v17 offset1:8
	ds_read2_b32 v[64:65], v17 offset0:66 offset1:74
	ds_read2_b32 v[66:67], v17 offset0:99 offset1:107
	ds_read2_b32 v[68:69], v17 offset0:132 offset1:140
	ds_read2_b32 v[70:71], v17 offset0:165 offset1:173
	ds_read2_b32 v[72:73], v17 offset0:198 offset1:206
	ds_read2_b32 v[74:75], v17 offset0:231 offset1:239
	s_waitcnt lgkmcnt(7)
	v_bfe_u32 v55, v60, 16, 1
	s_waitcnt lgkmcnt(6)
	v_bfe_u32 v0, v62, 16, 1
	v_add3_u32 v0, v62, v0, s92
	v_lshrrev_b32_e32 v0, 16, v0
	v_add3_u32 v55, v60, v55, s92
	v_and_or_b32 v56, v55, s1, v0
	s_waitcnt lgkmcnt(5)
	v_bfe_u32 v0, v64, 16, 1
	v_add3_u32 v0, v64, v0, s92
	s_waitcnt lgkmcnt(4)
	v_bfe_u32 v55, v66, 16, 1
	v_lshrrev_b32_e32 v0, 16, v0
	v_add3_u32 v55, v66, v55, s92
	v_and_or_b32 v57, v55, s1, v0
	s_waitcnt lgkmcnt(3)
	v_bfe_u32 v0, v68, 16, 1
	v_add3_u32 v0, v68, v0, s92
	s_waitcnt lgkmcnt(2)
	v_bfe_u32 v55, v70, 16, 1
	v_lshrrev_b32_e32 v0, 16, v0
	v_add3_u32 v55, v70, v55, s92
	v_and_or_b32 v58, v55, s1, v0
	s_waitcnt lgkmcnt(1)
	v_bfe_u32 v0, v72, 16, 1
	v_add3_u32 v0, v72, v0, s92
	s_waitcnt lgkmcnt(0)
	v_bfe_u32 v55, v74, 16, 1
	v_lshrrev_b32_e32 v0, 16, v0
	v_add3_u32 v55, v74, v55, s92
	v_and_or_b32 v59, v55, s1, v0
	v_bfe_u32 v0, v63, 16, 1
	v_lshl_add_u64 v[12:13], v[6:7], 0, s[58:59]
	v_add3_u32 v0, v63, v0, s92
	v_bfe_u32 v55, v61, 16, 1
	v_lshl_add_u64 v[76:77], v[12:13], 0, v[76:77]
	v_lshrrev_b32_e32 v0, 16, v0
	v_add3_u32 v55, v61, v55, s92
	global_store_dwordx4 v[76:77], v[56:59], off
	v_add_u32_e32 v60, s0, v18
	v_ashrrev_i32_e32 v61, 31, v60
	v_and_or_b32 v56, v55, s1, v0
	v_bfe_u32 v0, v65, 16, 1
	v_add3_u32 v0, v65, v0, s92
	v_bfe_u32 v55, v67, 16, 1
	v_lshrrev_b32_e32 v0, 16, v0
	v_add3_u32 v55, v67, v55, s92
	v_and_or_b32 v57, v55, s1, v0
	v_bfe_u32 v0, v69, 16, 1
	v_add3_u32 v0, v69, v0, s92
	v_bfe_u32 v55, v71, 16, 1
	v_lshrrev_b32_e32 v0, 16, v0
	v_add3_u32 v55, v71, v55, s92
	v_and_or_b32 v58, v55, s1, v0
	v_bfe_u32 v0, v73, 16, 1
	v_add3_u32 v0, v73, v0, s92
	v_bfe_u32 v55, v75, 16, 1
	v_lshrrev_b32_e32 v0, 16, v0
	v_add3_u32 v55, v75, v55, s92
	v_lshlrev_b64 v[60:61], 11, v[60:61]
	v_and_or_b32 v59, v55, s1, v0
	v_lshl_add_u64 v[60:61], v[12:13], 0, v[60:61]
	global_store_dwordx4 v[60:61], v[56:59], off
	ds_read2_b32 v[60:61], v17 offset0:49 offset1:57
	ds_read2_b32 v[62:63], v17 offset0:16 offset1:24
	ds_read2_b32 v[64:65], v17 offset0:82 offset1:90
	ds_read2_b32 v[66:67], v17 offset0:115 offset1:123
	ds_read2_b32 v[68:69], v17 offset0:148 offset1:156
	ds_read2_b32 v[70:71], v17 offset0:181 offset1:189
	ds_read2_b32 v[72:73], v17 offset0:214 offset1:222
	ds_read2_b32 v[74:75], v17 offset0:247 offset1:255
	s_waitcnt lgkmcnt(7)
	v_bfe_u32 v55, v60, 16, 1
	s_waitcnt lgkmcnt(6)
	v_bfe_u32 v0, v62, 16, 1
	v_add3_u32 v0, v62, v0, s92
	v_lshrrev_b32_e32 v0, 16, v0
	v_add3_u32 v55, v60, v55, s92
	v_and_or_b32 v56, v55, s1, v0
	s_waitcnt lgkmcnt(5)
	v_bfe_u32 v0, v64, 16, 1
	v_add3_u32 v0, v64, v0, s92
	s_waitcnt lgkmcnt(4)
	v_bfe_u32 v55, v66, 16, 1
	v_lshrrev_b32_e32 v0, 16, v0
	v_add3_u32 v55, v66, v55, s92
	v_and_or_b32 v57, v55, s1, v0
	s_waitcnt lgkmcnt(3)
	v_bfe_u32 v0, v68, 16, 1
	v_add3_u32 v0, v68, v0, s92
	s_waitcnt lgkmcnt(2)
	v_bfe_u32 v55, v70, 16, 1
	v_lshrrev_b32_e32 v0, 16, v0
	v_add3_u32 v55, v70, v55, s92
	v_and_or_b32 v58, v55, s1, v0
	s_waitcnt lgkmcnt(1)
	v_bfe_u32 v0, v72, 16, 1
	v_add3_u32 v0, v72, v0, s92
	s_waitcnt lgkmcnt(0)
	v_bfe_u32 v55, v74, 16, 1
	v_lshrrev_b32_e32 v0, 16, v0
	v_add3_u32 v55, v74, v55, s92
	v_add_u32_e32 v76, s0, v19
	v_and_or_b32 v59, v55, s1, v0
	v_ashrrev_i32_e32 v77, 31, v76
	v_bfe_u32 v0, v63, 16, 1
	v_lshlrev_b64 v[76:77], 11, v[76:77]
	v_add3_u32 v0, v63, v0, s92
	v_bfe_u32 v55, v61, 16, 1
	v_lshl_add_u64 v[76:77], v[12:13], 0, v[76:77]
	v_lshrrev_b32_e32 v0, 16, v0
	v_add3_u32 v55, v61, v55, s92
	global_store_dwordx4 v[76:77], v[56:59], off
	v_add_u32_e32 v60, s0, v20
	v_ashrrev_i32_e32 v61, 31, v60
	v_and_or_b32 v56, v55, s1, v0
	v_bfe_u32 v0, v65, 16, 1
	v_add3_u32 v0, v65, v0, s92
	v_bfe_u32 v55, v67, 16, 1
	v_lshrrev_b32_e32 v0, 16, v0
	v_add3_u32 v55, v67, v55, s92
	v_and_or_b32 v57, v55, s1, v0
	v_bfe_u32 v0, v69, 16, 1
	v_add3_u32 v0, v69, v0, s92
	v_bfe_u32 v55, v71, 16, 1
	v_lshrrev_b32_e32 v0, 16, v0
	v_add3_u32 v55, v71, v55, s92
	v_and_or_b32 v58, v55, s1, v0
	v_bfe_u32 v0, v73, 16, 1
	v_add3_u32 v0, v73, v0, s92
	v_bfe_u32 v55, v75, 16, 1
	v_lshrrev_b32_e32 v0, 16, v0
	v_add3_u32 v55, v75, v55, s92
	v_lshlrev_b64 v[60:61], 11, v[60:61]
	v_and_or_b32 v59, v55, s1, v0
	v_lshl_add_u64 v[12:13], v[12:13], 0, v[60:61]
	global_store_dwordx4 v[12:13], v[56:59], off
	s_waitcnt lgkmcnt(0)

.LBB0_308:
	s_andn2_b64 vcc, exec, s[0:1]
	s_cbranch_vccnz .LBB0_297
	s_mul_hi_i32 s0, s13, 0x38e38e39
	s_lshr_b32 s1, s0, 31
	s_ashr_i32 s0, s0, 4
	s_add_i32 s14, s0, s1
	s_mul_i32 s0, s14, 0xffffffb8
	s_load_dwordx4 s[16:19], s[48:49], 0x8
	s_add_i32 s0, s13, s0
	s_bfe_u32 s1, s0, 0x20001
	s_and_b32 s0, s0, 0x7fffff8
	s_and_b32 s4, s6, 4
	s_or_b32 s0, s4, s0
	s_or_b32 s1, s0, s1
	s_waitcnt lgkmcnt(0)
	s_add_u32 s4, s16, 0x1000
	s_addc_u32 s5, s17, 0
	s_lshl_b32 s0, s14, 6
	s_mulk_i32 s14, 0xf700
	s_add_i32 s14, s9, s14
	s_ashr_i32 s15, s14, 31
	s_lshl_b64 s[14:15], s[14:15], 2
	s_add_u32 s14, s18, s14
	s_addc_u32 s15, s19, s15
	v_lshlrev_b32_e32 v0, 2, v2
	v_lshl_add_u64 v[56:57], s[14:15], 0, v[0:1]
	s_mov_b64 s[14:15], 0x900000
	v_add_u32_e32 v12, s0, v3
	v_lshl_add_u64 v[66:67], v[56:57], 0, s[14:15]
	v_mad_i64_i32 v[56:57], s[14:15], v12, s95, v[66:67]
	v_add_u32_e32 v0, 2, v12
	global_load_dword v70, v[56:57], off nt
	v_mad_i64_i32 v[56:57], s[14:15], v0, s95, v[66:67]
	v_add_u32_e32 v0, 4, v12
	global_load_dword v71, v[56:57], off nt
	v_mad_i64_i32 v[56:57], s[14:15], v0, s95, v[66:67]
	v_add_u32_e32 v0, 6, v12
	global_load_dword v72, v[56:57], off nt
	v_mad_i64_i32 v[56:57], s[14:15], v0, s95, v[66:67]
	v_add_u32_e32 v0, 8, v12
	global_load_dword v73, v[56:57], off nt
	v_mad_i64_i32 v[56:57], s[14:15], v0, s95, v[66:67]
	v_add_u32_e32 v0, 10, v12
	global_load_dword v74, v[56:57], off nt
	v_mad_i64_i32 v[56:57], s[14:15], v0, s95, v[66:67]
	v_add_u32_e32 v0, 12, v12
	global_load_dword v75, v[56:57], off nt
	v_mad_i64_i32 v[56:57], s[14:15], v0, s95, v[66:67]
	v_add_u32_e32 v0, 14, v12
	global_load_dword v76, v[56:57], off nt
	v_mad_i64_i32 v[56:57], s[14:15], v0, s95, v[66:67]
	v_add_u32_e32 v0, 16, v12
	global_load_dword v77, v[56:57], off nt
	v_mad_i64_i32 v[56:57], s[14:15], v0, s95, v[66:67]
	v_add_u32_e32 v0, 18, v12
	global_load_dword v78, v[56:57], off nt
	v_mad_i64_i32 v[56:57], s[14:15], v0, s95, v[66:67]
	v_add_u32_e32 v0, 20, v12
	global_load_dword v79, v[56:57], off nt
	v_mad_i64_i32 v[56:57], s[14:15], v0, s95, v[66:67]
	v_add_u32_e32 v0, 22, v12
	global_load_dword v80, v[56:57], off nt
	v_mad_i64_i32 v[56:57], s[14:15], v0, s95, v[66:67]
	v_add_u32_e32 v0, 24, v12
	global_load_dword v81, v[56:57], off nt
	v_mad_i64_i32 v[56:57], s[14:15], v0, s95, v[66:67]
	v_add_u32_e32 v0, 26, v12
	global_load_dword v82, v[56:57], off nt
	v_mad_i64_i32 v[56:57], s[14:15], v0, s95, v[66:67]
	v_add_u32_e32 v0, 28, v12
	global_load_dword v83, v[56:57], off nt
	v_mad_i64_i32 v[56:57], s[14:15], v0, s95, v[66:67]
	v_add_u32_e32 v0, 30, v12
	global_load_dword v84, v[56:57], off nt
	v_mad_i64_i32 v[56:57], s[14:15], v0, s95, v[66:67]
	v_add_u32_e32 v0, 32, v12
	global_load_dword v85, v[56:57], off nt
	v_mad_i64_i32 v[56:57], s[14:15], v0, s95, v[66:67]
	v_add_u32_e32 v0, 34, v12
	global_load_dword v86, v[56:57], off nt
	v_mad_i64_i32 v[56:57], s[14:15], v0, s95, v[66:67]
	v_add_u32_e32 v0, 36, v12
	global_load_dword v87, v[56:57], off nt
	v_mad_i64_i32 v[56:57], s[14:15], v0, s95, v[66:67]
	v_add_u32_e32 v0, 38, v12
	global_load_dword v88, v[56:57], off nt
	v_mad_i64_i32 v[56:57], s[14:15], v0, s95, v[66:67]
	v_add_u32_e32 v0, 40, v12
	global_load_dword v89, v[56:57], off nt
	v_mad_i64_i32 v[56:57], s[14:15], v0, s95, v[66:67]
	v_add_u32_e32 v0, 42, v12
	global_load_dword v65, v[56:57], off nt
	v_mad_i64_i32 v[56:57], s[14:15], v0, s95, v[66:67]
	v_add_u32_e32 v0, 44, v12
	global_load_dword v64, v[56:57], off nt
	v_mad_i64_i32 v[56:57], s[14:15], v0, s95, v[66:67]
	v_add_u32_e32 v0, 46, v12
	global_load_dword v63, v[56:57], off nt
	v_mad_i64_i32 v[56:57], s[14:15], v0, s95, v[66:67]
	v_add_u32_e32 v0, 48, v12
	global_load_dword v62, v[56:57], off nt
	v_mad_i64_i32 v[56:57], s[14:15], v0, s95, v[66:67]
	v_add_u32_e32 v0, 50, v12
	global_load_dword v61, v[56:57], off nt
	v_mad_i64_i32 v[56:57], s[14:15], v0, s95, v[66:67]
	v_add_u32_e32 v0, 52, v12
	global_load_dword v60, v[56:57], off nt
	v_mad_i64_i32 v[56:57], s[14:15], v0, s95, v[66:67]
	v_add_u32_e32 v0, 54, v12
	global_load_dword v59, v[56:57], off nt
	v_mad_i64_i32 v[56:57], s[14:15], v0, s95, v[66:67]
	v_add_u32_e32 v0, 56, v12
	global_load_dword v58, v[56:57], off nt
	v_mad_i64_i32 v[56:57], s[14:15], v0, s95, v[66:67]
	v_add_u32_e32 v0, 58, v12
	v_ashrrev_i32_e32 v13, 31, v12
	v_mad_i64_i32 v[68:69], s[14:15], v0, s95, v[66:67]
	v_add_u32_e32 v0, 60, v12
	global_load_dword v57, v[56:57], off nt
	s_nop 0
	global_load_dword v56, v[68:69], off nt
	v_mad_i64_i32 v[68:69], s[14:15], v0, s95, v[66:67]
	v_add_u32_e32 v0, 62, v12
	v_lshlrev_b32_e32 v128, 2, v12
	global_load_dword v96, v128, s[4:5]
	v_add_lshl_u32 v128, s0, v21, 2
	global_load_dword v97, v128, s[4:5]
	v_add_lshl_u32 v128, s0, v23, 2
	global_load_dword v98, v128, s[4:5]
	v_add_lshl_u32 v128, s0, v24, 2
	global_load_dword v99, v128, s[4:5]
	v_add_lshl_u32 v128, s0, v25, 2
	global_load_dword v100, v128, s[4:5]
	v_add_lshl_u32 v128, s0, v26, 2
	global_load_dword v101, v128, s[4:5]
	v_add_lshl_u32 v128, s0, v27, 2
	global_load_dword v102, v128, s[4:5]
	v_add_lshl_u32 v128, s0, v28, 2
	global_load_dword v103, v128, s[4:5]
	v_add_lshl_u32 v128, s0, v30, 2
	global_load_dword v104, v128, s[4:5]
	v_add_lshl_u32 v128, s0, v31, 2
	global_load_dword v105, v128, s[4:5]
	v_add_lshl_u32 v128, s0, v32, 2
	global_load_dword v106, v128, s[4:5]
	v_add_lshl_u32 v128, s0, v33, 2
	global_load_dword v107, v128, s[4:5]
	v_add_lshl_u32 v128, s0, v34, 2
	global_load_dword v108, v128, s[4:5]
	v_add_lshl_u32 v128, s0, v35, 2
	global_load_dword v109, v128, s[4:5]
	v_add_lshl_u32 v128, s0, v37, 2
	global_load_dword v110, v128, s[4:5]
	v_add_lshl_u32 v128, s0, v38, 2
	global_load_dword v111, v128, s[4:5]
	v_add_lshl_u32 v128, s0, v39, 2
	global_load_dword v112, v128, s[4:5]
	v_add_lshl_u32 v128, s0, v40, 2
	global_load_dword v113, v128, s[4:5]
	v_add_lshl_u32 v128, s0, v41, 2
	global_load_dword v114, v128, s[4:5]
	v_add_lshl_u32 v128, s0, v42, 2
	global_load_dword v115, v128, s[4:5]
	v_add_lshl_u32 v128, s0, v43, 2
	global_load_dword v116, v128, s[4:5]
	v_add_lshl_u32 v128, s0, v44, 2
	global_load_dword v117, v128, s[4:5]
	v_add_lshl_u32 v128, s0, v45, 2
	global_load_dword v118, v128, s[4:5]
	v_add_lshl_u32 v128, s0, v46, 2
	global_load_dword v119, v128, s[4:5]
	v_add_lshl_u32 v128, s0, v47, 2
	global_load_dword v120, v128, s[4:5]
	v_add_lshl_u32 v128, s0, v48, 2
	global_load_dword v121, v128, s[4:5]
	v_add_lshl_u32 v128, s0, v49, 2
	global_load_dword v122, v128, s[4:5]
	v_add_lshl_u32 v128, s0, v50, 2
	global_load_dword v123, v128, s[4:5]
	v_add_lshl_u32 v128, s0, v51, 2
	global_load_dword v124, v128, s[4:5]
	v_add_lshl_u32 v128, s0, v52, 2
	global_load_dword v125, v128, s[4:5]
	v_add_lshl_u32 v128, s0, v53, 2
	global_load_dword v126, v128, s[4:5]
	v_add_lshl_u32 v128, s0, v54, 2
	global_load_dword v127, v128, s[4:5]
	v_lshl_add_u64 v[12:13], v[12:13], 2, s[4:5]
	v_add_u32_e32 v13, v14, v15
	v_mad_i64_i32 v[66:67], s[14:15], v0, s95, v[66:67]
	global_load_dword v55, v[68:69], off nt
	global_load_dword v0, v[66:67], off nt
	v_add_u32_e32 v67, v14, v22
	s_waitcnt vmcnt(0)
	v_mov_b32_e32 v12, v96
	v_mul_f32_e32 v12, v70, v12
	ds_write_b32 v13, v12
	v_add_u32_e32 v12, s0, v21
	v_ashrrev_i32_e32 v13, 31, v12
	v_lshl_add_u64 v[12:13], v[12:13], 2, s[4:5]
	v_mov_b32_e32 v12, v97
	s_waitcnt vmcnt(0)
	v_mul_f32_e32 v66, v71, v12
	v_add_u32_e32 v12, s0, v23
	v_ashrrev_i32_e32 v13, 31, v12
	v_lshl_add_u64 v[12:13], v[12:13], 2, s[4:5]
	v_mov_b32_e32 v12, v98
	s_waitcnt vmcnt(0)
	v_mul_f32_e32 v12, v72, v12
	ds_write2_b32 v67, v66, v12 offset1:66
	v_add_u32_e32 v12, s0, v24
	v_ashrrev_i32_e32 v13, 31, v12
	v_lshl_add_u64 v[12:13], v[12:13], 2, s[4:5]
	v_mov_b32_e32 v12, v99
	s_waitcnt vmcnt(0)
	v_mul_f32_e32 v66, v73, v12
	v_add_u32_e32 v12, s0, v25
	v_ashrrev_i32_e32 v13, 31, v12
	v_lshl_add_u64 v[12:13], v[12:13], 2, s[4:5]
	v_mov_b32_e32 v12, v100
	s_waitcnt vmcnt(0)
	v_mul_f32_e32 v12, v74, v12
	ds_write2_b32 v67, v66, v12 offset0:132 offset1:198
	v_add_u32_e32 v12, s0, v26
	v_ashrrev_i32_e32 v13, 31, v12
	v_lshl_add_u64 v[12:13], v[12:13], 2, s[4:5]
	v_mov_b32_e32 v12, v101
	s_waitcnt vmcnt(0)
	v_mul_f32_e32 v66, v75, v12
	v_add_u32_e32 v12, s0, v27
	v_ashrrev_i32_e32 v13, 31, v12
	v_lshl_add_u64 v[12:13], v[12:13], 2, s[4:5]
	v_mov_b32_e32 v12, v102
	v_add_u32_e32 v13, 0x400, v67
	v_add_u32_e32 v67, v14, v29
	s_waitcnt vmcnt(0)
	v_mul_f32_e32 v12, v76, v12
	ds_write2_b32 v13, v66, v12 offset0:8 offset1:74
	v_add_u32_e32 v12, s0, v28
	v_ashrrev_i32_e32 v13, 31, v12
	v_lshl_add_u64 v[12:13], v[12:13], 2, s[4:5]
	v_mov_b32_e32 v12, v103
	s_waitcnt vmcnt(0)
	v_mul_f32_e32 v66, v77, v12
	v_add_u32_e32 v12, s0, v30
	v_ashrrev_i32_e32 v13, 31, v12
	v_lshl_add_u64 v[12:13], v[12:13], 2, s[4:5]
	v_mov_b32_e32 v12, v104
	s_waitcnt vmcnt(0)
	v_mul_f32_e32 v12, v78, v12
	ds_write2_b32 v67, v66, v12 offset1:66
	v_add_u32_e32 v12, s0, v31
	v_ashrrev_i32_e32 v13, 31, v12
	v_lshl_add_u64 v[12:13], v[12:13], 2, s[4:5]
	v_mov_b32_e32 v12, v105
	s_waitcnt vmcnt(0)
	v_mul_f32_e32 v66, v79, v12
	v_add_u32_e32 v12, s0, v32
	v_ashrrev_i32_e32 v13, 31, v12
	v_lshl_add_u64 v[12:13], v[12:13], 2, s[4:5]
	v_mov_b32_e32 v12, v106
	s_waitcnt vmcnt(0)
	v_mul_f32_e32 v12, v80, v12
	ds_write2_b32 v67, v66, v12 offset0:132 offset1:198
	v_add_u32_e32 v12, s0, v33
	v_ashrrev_i32_e32 v13, 31, v12
	v_lshl_add_u64 v[12:13], v[12:13], 2, s[4:5]
	v_mov_b32_e32 v12, v107
	s_waitcnt vmcnt(0)
	v_mul_f32_e32 v66, v81, v12
	v_add_u32_e32 v12, s0, v34
	v_ashrrev_i32_e32 v13, 31, v12
	v_lshl_add_u64 v[12:13], v[12:13], 2, s[4:5]
	v_mov_b32_e32 v12, v108
	v_add_u32_e32 v13, 0x400, v67
	s_waitcnt vmcnt(0)
	v_mul_f32_e32 v12, v82, v12
	ds_write2_b32 v13, v66, v12 offset0:8 offset1:74
	v_add_u32_e32 v12, s0, v35
	v_add_u32_e32 v66, s0, v37
	v_ashrrev_i32_e32 v13, 31, v12
	v_ashrrev_i32_e32 v67, 31, v66
	v_lshl_add_u64 v[12:13], v[12:13], 2, s[4:5]
	v_lshl_add_u64 v[66:67], v[66:67], 2, s[4:5]
	v_mov_b32_e32 v12, v109
	s_nop 0
	v_mov_b32_e32 v66, v110
	s_waitcnt vmcnt(1)
	v_mul_f32_e32 v13, v83, v12
	v_add_u32_e32 v12, v14, v36
	s_waitcnt vmcnt(0)
	v_mul_f32_e32 v66, v84, v66
	ds_write2_b32 v12, v13, v66 offset1:66
	v_add_u32_e32 v66, s0, v38
	v_ashrrev_i32_e32 v67, 31, v66
	v_lshl_add_u64 v[66:67], v[66:67], 2, s[4:5]
	v_mov_b32_e32 v13, v111
	v_add_u32_e32 v66, s0, v39
	v_ashrrev_i32_e32 v67, 31, v66
	v_lshl_add_u64 v[66:67], v[66:67], 2, s[4:5]
	v_mov_b32_e32 v66, v112
	v_add_u32_e32 v68, 0x400, v12
	s_waitcnt vmcnt(1)
	v_mul_f32_e32 v13, v85, v13
	s_waitcnt vmcnt(0)
	v_mul_f32_e32 v66, v86, v66
	ds_write2_b32 v12, v13, v66 offset0:132 offset1:198
	v_add_u32_e32 v66, s0, v40
	v_ashrrev_i32_e32 v67, 31, v66
	v_lshl_add_u64 v[66:67], v[66:67], 2, s[4:5]
	v_mov_b32_e32 v13, v113
	v_add_u32_e32 v66, s0, v41
	v_ashrrev_i32_e32 v67, 31, v66
	v_lshl_add_u64 v[66:67], v[66:67], 2, s[4:5]
	v_mov_b32_e32 v66, v114
	s_waitcnt vmcnt(1)
	v_mul_f32_e32 v13, v87, v13
	s_waitcnt vmcnt(0)
	v_mul_f32_e32 v66, v88, v66
	ds_write2_b32 v68, v13, v66 offset0:8 offset1:74
	v_add_u32_e32 v66, s0, v42
	v_ashrrev_i32_e32 v67, 31, v66
	v_lshl_add_u64 v[66:67], v[66:67], 2, s[4:5]
	v_mov_b32_e32 v13, v115
	v_add_u32_e32 v66, s0, v43
	v_ashrrev_i32_e32 v67, 31, v66
	v_lshl_add_u64 v[66:67], v[66:67], 2, s[4:5]
	v_mov_b32_e32 v66, v116
	s_waitcnt vmcnt(1)
	v_mul_f32_e32 v13, v89, v13
	s_waitcnt vmcnt(0)
	v_mul_f32_e32 v65, v65, v66
	v_add_u32_e32 v66, s0, v44
	v_ashrrev_i32_e32 v67, 31, v66
	v_lshl_add_u64 v[66:67], v[66:67], 2, s[4:5]
	ds_write2_b32 v68, v13, v65 offset0:140 offset1:206
	v_mov_b32_e32 v13, v117
	v_add_u32_e32 v66, 0x800, v12
	s_waitcnt vmcnt(0)
	v_mul_f32_e32 v13, v64, v13
	v_add_u32_e32 v64, s0, v45
	v_ashrrev_i32_e32 v65, 31, v64
	v_lshl_add_u64 v[64:65], v[64:65], 2, s[4:5]
	v_mov_b32_e32 v64, v118
	s_waitcnt vmcnt(0)
	v_mul_f32_e32 v63, v63, v64
	v_add_u32_e32 v64, s0, v46
	v_ashrrev_i32_e32 v65, 31, v64
	v_lshl_add_u64 v[64:65], v[64:65], 2, s[4:5]
	ds_write2_b32 v66, v13, v63 offset0:16 offset1:82
	v_mov_b32_e32 v13, v119
	s_waitcnt vmcnt(0)
	v_mul_f32_e32 v13, v62, v13
	v_add_u32_e32 v62, s0, v47
	v_ashrrev_i32_e32 v63, 31, v62
	v_lshl_add_u64 v[62:63], v[62:63], 2, s[4:5]
	v_mov_b32_e32 v62, v120
	s_waitcnt vmcnt(0)
	v_mul_f32_e32 v61, v61, v62
	v_add_u32_e32 v62, s0, v48
	v_ashrrev_i32_e32 v63, 31, v62
	v_lshl_add_u64 v[62:63], v[62:63], 2, s[4:5]
	ds_write2_b32 v66, v13, v61 offset0:148 offset1:214
	v_mov_b32_e32 v13, v121
	v_add_u32_e32 v62, 0xc00, v12
	s_waitcnt vmcnt(0)
	v_mul_f32_e32 v13, v60, v13
	v_add_u32_e32 v60, s0, v49
	v_ashrrev_i32_e32 v61, 31, v60
	v_lshl_add_u64 v[60:61], v[60:61], 2, s[4:5]
	v_mov_b32_e32 v60, v122
	s_waitcnt vmcnt(0)
	v_mul_f32_e32 v59, v59, v60
	v_add_u32_e32 v60, s0, v50
	v_ashrrev_i32_e32 v61, 31, v60
	v_lshl_add_u64 v[60:61], v[60:61], 2, s[4:5]
	ds_write2_b32 v62, v13, v59 offset0:24 offset1:90
	v_mov_b32_e32 v13, v123
	s_waitcnt vmcnt(0)
	v_mul_f32_e32 v13, v58, v13
	v_add_u32_e32 v58, s0, v51
	v_ashrrev_i32_e32 v59, 31, v58
	v_lshl_add_u64 v[58:59], v[58:59], 2, s[4:5]
	v_mov_b32_e32 v58, v124
	s_waitcnt vmcnt(0)
	v_mul_f32_e32 v57, v57, v58
	v_add_u32_e32 v58, s0, v52
	v_ashrrev_i32_e32 v59, 31, v58
	v_lshl_add_u64 v[58:59], v[58:59], 2, s[4:5]
	ds_write2_b32 v62, v13, v57 offset0:156 offset1:222
	v_mov_b32_e32 v13, v125
	s_waitcnt vmcnt(0)
	v_mul_f32_e32 v13, v56, v13
	v_add_u32_e32 v56, s0, v53
	v_ashrrev_i32_e32 v57, 31, v56
	v_lshl_add_u64 v[56:57], v[56:57], 2, s[4:5]
	v_mov_b32_e32 v56, v126
	s_waitcnt vmcnt(0)
	v_mul_f32_e32 v55, v55, v56
	v_add_u32_e32 v56, 0x1000, v12
	ds_write2_b32 v56, v13, v55 offset0:32 offset1:98
	v_add_u32_e32 v56, s0, v54
	v_ashrrev_i32_e32 v57, 31, v56
	v_lshl_add_u64 v[56:57], v[56:57], 2, s[4:5]
	v_mov_b32_e32 v13, v127
	s_lshl_b32 s4, s1, 5
	s_ashr_i32 s1, s0, 31
	v_add_u32_e32 v76, s4, v16
	v_ashrrev_i32_e32 v77, 31, v76
	v_lshlrev_b64 v[76:77], 11, v[76:77]
	s_waitcnt vmcnt(0)
	v_mul_f32_e32 v0, v0, v13
	ds_write_b32 v12, v0 offset:4752
	s_waitcnt lgkmcnt(0)
	ds_read2_b32 v[60:61], v17 offset0:33 offset1:41
	ds_read2_b32 v[62:63], v17 offset1:8
	ds_read2_b32 v[64:65], v17 offset0:66 offset1:74
	ds_read2_b32 v[66:67], v17 offset0:99 offset1:107
	v_lshl_add_u64 v[12:13], s[0:1], 1, v[10:11]
	s_mov_b32 s0, 0xffff0000
	s_waitcnt lgkmcnt(3)
	v_bfe_u32 v55, v60, 16, 1
	s_waitcnt lgkmcnt(2)
	v_bfe_u32 v0, v62, 16, 1
	v_add3_u32 v0, v62, v0, s92
	v_lshrrev_b32_e32 v0, 16, v0
	v_add3_u32 v55, v60, v55, s92
	ds_read2_b32 v[68:69], v17 offset0:132 offset1:140
	ds_read2_b32 v[70:71], v17 offset0:165 offset1:173
	v_and_or_b32 v56, v55, s0, v0
	s_waitcnt lgkmcnt(3)
	v_bfe_u32 v0, v64, 16, 1
	v_add3_u32 v0, v64, v0, s92
	s_waitcnt lgkmcnt(2)
	v_bfe_u32 v55, v66, 16, 1
	v_lshrrev_b32_e32 v0, 16, v0
	v_add3_u32 v55, v66, v55, s92
	ds_read2_b32 v[72:73], v17 offset0:198 offset1:206
	ds_read2_b32 v[74:75], v17 offset0:231 offset1:239
	v_and_or_b32 v57, v55, s0, v0
	s_waitcnt lgkmcnt(3)
	v_bfe_u32 v0, v68, 16, 1
	v_add3_u32 v0, v68, v0, s92
	s_waitcnt lgkmcnt(2)
	v_bfe_u32 v55, v70, 16, 1
	v_lshrrev_b32_e32 v0, 16, v0
	v_add3_u32 v55, v70, v55, s92
	v_and_or_b32 v58, v55, s0, v0
	s_waitcnt lgkmcnt(1)
	v_bfe_u32 v0, v72, 16, 1
	v_add3_u32 v0, v72, v0, s92
	s_waitcnt lgkmcnt(0)
	v_bfe_u32 v55, v74, 16, 1
	v_lshrrev_b32_e32 v0, 16, v0
	v_add3_u32 v55, v74, v55, s92
	v_and_or_b32 v59, v55, s0, v0
	v_bfe_u32 v0, v63, 16, 1
	v_add3_u32 v0, v63, v0, s92
	v_bfe_u32 v55, v61, 16, 1
	v_lshl_add_u64 v[76:77], v[12:13], 0, v[76:77]
	v_lshrrev_b32_e32 v0, 16, v0
	v_add3_u32 v55, v61, v55, s92
	global_store_dwordx4 v[76:77], v[56:59], off
	v_add_u32_e32 v60, s4, v18
	v_ashrrev_i32_e32 v61, 31, v60
	v_and_or_b32 v56, v55, s0, v0
	v_bfe_u32 v0, v65, 16, 1
	v_add3_u32 v0, v65, v0, s92
	v_bfe_u32 v55, v67, 16, 1
	v_lshrrev_b32_e32 v0, 16, v0
	v_add3_u32 v55, v67, v55, s92
	v_and_or_b32 v57, v55, s0, v0
	v_bfe_u32 v0, v69, 16, 1
	v_add3_u32 v0, v69, v0, s92
	v_bfe_u32 v55, v71, 16, 1
	v_lshrrev_b32_e32 v0, 16, v0
	v_add3_u32 v55, v71, v55, s92
	v_and_or_b32 v58, v55, s0, v0
	v_bfe_u32 v0, v73, 16, 1
	v_add3_u32 v0, v73, v0, s92
	v_bfe_u32 v55, v75, 16, 1
	v_lshrrev_b32_e32 v0, 16, v0
	v_add3_u32 v55, v75, v55, s92
	v_lshlrev_b64 v[60:61], 11, v[60:61]
	v_and_or_b32 v59, v55, s0, v0
	v_lshl_add_u64 v[60:61], v[12:13], 0, v[60:61]
	global_store_dwordx4 v[60:61], v[56:59], off
	ds_read2_b32 v[60:61], v17 offset0:49 offset1:57
	ds_read2_b32 v[62:63], v17 offset0:16 offset1:24
	ds_read2_b32 v[64:65], v17 offset0:82 offset1:90
	ds_read2_b32 v[66:67], v17 offset0:115 offset1:123
	ds_read2_b32 v[68:69], v17 offset0:148 offset1:156
	ds_read2_b32 v[70:71], v17 offset0:181 offset1:189
	ds_read2_b32 v[72:73], v17 offset0:214 offset1:222
	ds_read2_b32 v[74:75], v17 offset0:247 offset1:255
	s_waitcnt lgkmcnt(7)
	v_bfe_u32 v55, v60, 16, 1
	s_waitcnt lgkmcnt(6)
	v_bfe_u32 v0, v62, 16, 1
	v_add3_u32 v0, v62, v0, s92
	v_lshrrev_b32_e32 v0, 16, v0
	v_add3_u32 v55, v60, v55, s92
	v_and_or_b32 v56, v55, s0, v0
	s_waitcnt lgkmcnt(5)
	v_bfe_u32 v0, v64, 16, 1
	v_add3_u32 v0, v64, v0, s92
	s_waitcnt lgkmcnt(4)
	v_bfe_u32 v55, v66, 16, 1
	v_lshrrev_b32_e32 v0, 16, v0
	v_add3_u32 v55, v66, v55, s92
	v_and_or_b32 v57, v55, s0, v0
	s_waitcnt lgkmcnt(3)
	v_bfe_u32 v0, v68, 16, 1
	v_add3_u32 v0, v68, v0, s92
	s_waitcnt lgkmcnt(2)
	v_bfe_u32 v55, v70, 16, 1
	v_lshrrev_b32_e32 v0, 16, v0
	v_add3_u32 v55, v70, v55, s92
	v_and_or_b32 v58, v55, s0, v0
	s_waitcnt lgkmcnt(1)
	v_bfe_u32 v0, v72, 16, 1
	v_add3_u32 v0, v72, v0, s92
	s_waitcnt lgkmcnt(0)
	v_bfe_u32 v55, v74, 16, 1
	v_lshrrev_b32_e32 v0, 16, v0
	v_add3_u32 v55, v74, v55, s92
	v_add_u32_e32 v76, s4, v19
	v_and_or_b32 v59, v55, s0, v0
	v_ashrrev_i32_e32 v77, 31, v76
	v_bfe_u32 v0, v63, 16, 1
	v_lshlrev_b64 v[76:77], 11, v[76:77]
	v_add3_u32 v0, v63, v0, s92
	v_bfe_u32 v55, v61, 16, 1
	v_lshl_add_u64 v[76:77], v[12:13], 0, v[76:77]
	v_lshrrev_b32_e32 v0, 16, v0
	v_add3_u32 v55, v61, v55, s92
	global_store_dwordx4 v[76:77], v[56:59], off
	v_add_u32_e32 v60, s4, v20
	v_ashrrev_i32_e32 v61, 31, v60
	v_and_or_b32 v56, v55, s0, v0
	v_bfe_u32 v0, v65, 16, 1
	v_add3_u32 v0, v65, v0, s92
	v_bfe_u32 v55, v67, 16, 1
	v_lshrrev_b32_e32 v0, 16, v0
	v_add3_u32 v55, v67, v55, s92
	v_and_or_b32 v57, v55, s0, v0
	v_bfe_u32 v0, v69, 16, 1
	v_add3_u32 v0, v69, v0, s92
	v_bfe_u32 v55, v71, 16, 1
	v_lshrrev_b32_e32 v0, 16, v0
	v_add3_u32 v55, v71, v55, s92
	v_and_or_b32 v58, v55, s0, v0
	v_bfe_u32 v0, v73, 16, 1
	v_add3_u32 v0, v73, v0, s92
	v_bfe_u32 v55, v75, 16, 1
	v_lshrrev_b32_e32 v0, 16, v0
	v_add3_u32 v55, v75, v55, s92
	v_lshlrev_b64 v[60:61], 11, v[60:61]
	v_and_or_b32 v59, v55, s0, v0
	v_lshl_add_u64 v[12:13], v[12:13], 0, v[60:61]
	global_store_dwordx4 v[12:13], v[56:59], off
	s_waitcnt lgkmcnt(0)
	s_branch .LBB0_297
